# FFN up K-loops: second-half A-fragment reads addressed from the persistent base register with an immediate offset (2 VALU per iteration removed); remaining s_setprio in the unrolled GEMM tails removed
# baseline (speedup 1.0000x reference)
.LBB0_170:
	ds_read_b128 v[148:151], v165
	ds_read_b128 v[152:155], v165 offset:1024
	ds_read_b128 v[156:159], v165 offset:2048
	ds_read_b128 v[160:163], v165 offset:3072
	ds_read_b128 v[170:173], v166
	ds_read_b128 v[174:177], v166 offset:1024
	ds_read_b128 v[178:181], v166 offset:2048
	ds_read_b128 v[182:185], v166 offset:3072
	s_add_u32 s28, s52, 0xfffc0080
	s_addc_u32 s29, s53, -1
	s_cmp_eq_u32 s73, 12
	s_cselect_b32 s31, s15, s29
	s_cselect_b32 s30, s69, s28
	s_cselect_b32 s29, s13, s72
	s_cselect_b32 s28, s70, s71
	s_add_i32 m0, s21, 0xc000
	ds_read_b128 v[186:189], v167
	ds_read_b128 v[190:193], v167 offset:1024
	ds_read_b128 v[194:197], v167 offset:2048
	ds_read_b128 v[198:201], v167 offset:3072
	ds_read_b128 v[202:205], v167 offset:4096
	ds_read_b128 v[206:209], v167 offset:5120
	ds_read_b128 v[210:213], v167 offset:6144
	ds_read_b128 v[214:217], v167 offset:7168
	global_load_lds_dwordx4 v140, s[52:53]
	s_add_i32 m0, s21, 0xe000
	s_nop 0
	global_load_lds_dwordx4 v142, s[52:53]
	s_waitcnt vmcnt(8)
	s_waitcnt lgkmcnt(0)
	s_barrier
	v_mfma_f32_16x16x32_bf16 v[126:129], v[148:151], v[186:189], v[126:129]
	v_mfma_f32_16x16x32_bf16 v[118:121], v[156:159], v[186:189], v[118:121]
	v_mfma_f32_16x16x32_bf16 v[110:113], v[148:151], v[194:197], v[110:113]
	v_mfma_f32_16x16x32_bf16 v[102:105], v[156:159], v[194:197], v[102:105]
	v_mfma_f32_16x16x32_bf16 v[94:97], v[148:151], v[202:205], v[94:97]
	v_mfma_f32_16x16x32_bf16 v[86:89], v[156:159], v[202:205], v[86:89]
	v_mfma_f32_16x16x32_bf16 v[78:81], v[148:151], v[210:213], v[78:81]
	v_mfma_f32_16x16x32_bf16 v[70:73], v[156:159], v[210:213], v[70:73]
	v_mfma_f32_16x16x32_bf16 v[126:129], v[152:155], v[190:193], v[126:129]
	v_mfma_f32_16x16x32_bf16 v[118:121], v[160:163], v[190:193], v[118:121]
	v_mfma_f32_16x16x32_bf16 v[110:113], v[152:155], v[198:201], v[110:113]
	v_mfma_f32_16x16x32_bf16 v[102:105], v[160:163], v[198:201], v[102:105]
	v_mfma_f32_16x16x32_bf16 v[94:97], v[152:155], v[206:209], v[94:97]
	v_mfma_f32_16x16x32_bf16 v[86:89], v[160:163], v[206:209], v[86:89]
	v_mfma_f32_16x16x32_bf16 v[78:81], v[152:155], v[214:217], v[78:81]
	v_mfma_f32_16x16x32_bf16 v[70:73], v[160:163], v[214:217], v[70:73]
	v_mfma_f32_16x16x32_bf16 v[122:125], v[170:173], v[186:189], v[122:125]
	v_mfma_f32_16x16x32_bf16 v[114:117], v[178:181], v[186:189], v[114:117]
	v_mfma_f32_16x16x32_bf16 v[106:109], v[170:173], v[194:197], v[106:109]
	v_mfma_f32_16x16x32_bf16 v[98:101], v[178:181], v[194:197], v[98:101]
	v_mfma_f32_16x16x32_bf16 v[90:93], v[170:173], v[202:205], v[90:93]
	v_mfma_f32_16x16x32_bf16 v[82:85], v[178:181], v[202:205], v[82:85]
	v_mfma_f32_16x16x32_bf16 v[74:77], v[170:173], v[210:213], v[74:77]
	v_mfma_f32_16x16x32_bf16 v[66:69], v[178:181], v[210:213], v[66:69]
	v_mfma_f32_16x16x32_bf16 v[122:125], v[174:177], v[190:193], v[122:125]
	v_mfma_f32_16x16x32_bf16 v[114:117], v[182:185], v[190:193], v[114:117]
	v_mfma_f32_16x16x32_bf16 v[106:109], v[174:177], v[198:201], v[106:109]
	v_mfma_f32_16x16x32_bf16 v[98:101], v[182:185], v[198:201], v[98:101]
	v_mfma_f32_16x16x32_bf16 v[90:93], v[174:177], v[206:209], v[90:93]
	v_mfma_f32_16x16x32_bf16 v[82:85], v[182:185], v[206:209], v[82:85]
	v_mfma_f32_16x16x32_bf16 v[74:77], v[174:177], v[214:217], v[74:77]
	v_mfma_f32_16x16x32_bf16 v[66:69], v[182:185], v[214:217], v[66:69]
	s_barrier
	s_add_i32 s74, s59, s24
	s_mov_b32 m0, s74
	ds_read_b128 v[186:189], v167 offset:16384
	ds_read_b128 v[190:193], v167 offset:17408
	ds_read_b128 v[194:197], v167 offset:18432
	ds_read_b128 v[198:201], v167 offset:19456
	ds_read_b128 v[202:205], v167 offset:20480
	ds_read_b128 v[206:209], v167 offset:21504
	ds_read_b128 v[210:213], v167 offset:22528
	ds_read_b128 v[214:217], v167 offset:23552
	global_load_lds_dwordx4 v134, s[28:29]
	s_add_i32 m0, s74, 0x2000
	s_add_u32 s74, s28, 0x40000
	s_addc_u32 s75, s29, 0
	s_add_i32 s76, s66, s24
	global_load_lds_dwordx4 v130, s[28:29]
	s_mov_b32 m0, s76
	s_nop 0
	global_load_lds_dwordx4 v134, s[74:75]
	s_add_i32 m0, s76, 0x2000
	s_nop 0
	global_load_lds_dwordx4 v130, s[74:75]
	s_mov_b32 m0, s21
	s_nop 0
	global_load_lds_dwordx4 v136, s[30:31]
	s_mov_b32 m0, s34
	s_nop 0
	global_load_lds_dwordx4 v132, s[30:31]
	s_waitcnt vmcnt(8)
	s_waitcnt lgkmcnt(0)
	s_barrier
	v_mfma_f32_16x16x32_bf16 v[62:65], v[148:151], v[186:189], v[62:65]
	v_mfma_f32_16x16x32_bf16 v[54:57], v[156:159], v[186:189], v[54:57]
	v_mfma_f32_16x16x32_bf16 v[46:49], v[148:151], v[194:197], v[46:49]
	v_mfma_f32_16x16x32_bf16 v[38:41], v[156:159], v[194:197], v[38:41]
	v_mfma_f32_16x16x32_bf16 v[30:33], v[148:151], v[202:205], v[30:33]
	v_mfma_f32_16x16x32_bf16 v[22:25], v[156:159], v[202:205], v[22:25]
	v_mfma_f32_16x16x32_bf16 v[14:17], v[148:151], v[210:213], v[14:17]
	v_mfma_f32_16x16x32_bf16 v[6:9], v[156:159], v[210:213], v[6:9]
	v_mfma_f32_16x16x32_bf16 v[62:65], v[152:155], v[190:193], v[62:65]
	v_mfma_f32_16x16x32_bf16 v[54:57], v[160:163], v[190:193], v[54:57]
	v_mfma_f32_16x16x32_bf16 v[46:49], v[152:155], v[198:201], v[46:49]
	v_mfma_f32_16x16x32_bf16 v[38:41], v[160:163], v[198:201], v[38:41]
	v_mfma_f32_16x16x32_bf16 v[30:33], v[152:155], v[206:209], v[30:33]
	v_mfma_f32_16x16x32_bf16 v[22:25], v[160:163], v[206:209], v[22:25]
	v_mfma_f32_16x16x32_bf16 v[14:17], v[152:155], v[214:217], v[14:17]
	v_mfma_f32_16x16x32_bf16 v[6:9], v[160:163], v[214:217], v[6:9]
	v_mfma_f32_16x16x32_bf16 v[58:61], v[170:173], v[186:189], v[58:61]
	v_mfma_f32_16x16x32_bf16 v[50:53], v[178:181], v[186:189], v[50:53]
	v_mfma_f32_16x16x32_bf16 v[42:45], v[170:173], v[194:197], v[42:45]
	v_mfma_f32_16x16x32_bf16 v[34:37], v[178:181], v[194:197], v[34:37]
	v_mfma_f32_16x16x32_bf16 v[26:29], v[170:173], v[202:205], v[26:29]
	v_mfma_f32_16x16x32_bf16 v[18:21], v[178:181], v[202:205], v[18:21]
	v_mfma_f32_16x16x32_bf16 v[10:13], v[170:173], v[210:213], v[10:13]
	v_mfma_f32_16x16x32_bf16 v[2:5], v[178:181], v[210:213], v[2:5]
	v_mfma_f32_16x16x32_bf16 v[58:61], v[174:177], v[190:193], v[58:61]
	v_mfma_f32_16x16x32_bf16 v[50:53], v[182:185], v[190:193], v[50:53]
	v_mfma_f32_16x16x32_bf16 v[42:45], v[174:177], v[198:201], v[42:45]
	v_mfma_f32_16x16x32_bf16 v[34:37], v[182:185], v[198:201], v[34:37]
	v_mfma_f32_16x16x32_bf16 v[26:29], v[174:177], v[206:209], v[26:29]
	v_mfma_f32_16x16x32_bf16 v[18:21], v[182:185], v[206:209], v[18:21]
	v_mfma_f32_16x16x32_bf16 v[10:13], v[174:177], v[214:217], v[10:13]
	v_mfma_f32_16x16x32_bf16 v[2:5], v[182:185], v[214:217], v[2:5]
	s_barrier
	s_add_i32 s74, 0, 0x18000
	s_add_i32 s75, 0, 0x1c000
	ds_read_b128 v[148:151], v165 offset:32768
	ds_read_b128 v[152:155], v165 offset:33792
	ds_read_b128 v[156:159], v165 offset:34816
	ds_read_b128 v[160:163], v165 offset:35840
	ds_read_b128 v[170:173], v166 offset:32768
	ds_read_b128 v[174:177], v166 offset:33792
	ds_read_b128 v[178:181], v166 offset:34816
	ds_read_b128 v[182:185], v166 offset:35840
	s_add_u32 s98, s30, 0x40000
	s_addc_u32 s99, s31, 0
	s_mov_b32 m0, s35
	ds_read_b128 v[186:189], v167 offset:32768
	ds_read_b128 v[190:193], v167 offset:33792
	ds_read_b128 v[194:197], v167 offset:34816
	ds_read_b128 v[198:201], v167 offset:35840
	ds_read_b128 v[202:205], v167 offset:36864
	ds_read_b128 v[206:209], v167 offset:37888
	ds_read_b128 v[210:213], v167 offset:38912
	ds_read_b128 v[214:217], v167 offset:39936
	global_load_lds_dwordx4 v136, s[98:99]
	s_mov_b32 m0, s54
	s_nop 0
	global_load_lds_dwordx4 v132, s[98:99]
	s_waitcnt vmcnt(8)
	s_waitcnt lgkmcnt(0)
	s_barrier
	v_mfma_f32_16x16x32_bf16 v[126:129], v[148:151], v[186:189], v[126:129]
	v_mfma_f32_16x16x32_bf16 v[118:121], v[156:159], v[186:189], v[118:121]
	v_mfma_f32_16x16x32_bf16 v[110:113], v[148:151], v[194:197], v[110:113]
	v_mfma_f32_16x16x32_bf16 v[102:105], v[156:159], v[194:197], v[102:105]
	v_mfma_f32_16x16x32_bf16 v[94:97], v[148:151], v[202:205], v[94:97]
	v_mfma_f32_16x16x32_bf16 v[86:89], v[156:159], v[202:205], v[86:89]
	v_mfma_f32_16x16x32_bf16 v[78:81], v[148:151], v[210:213], v[78:81]
	v_mfma_f32_16x16x32_bf16 v[70:73], v[156:159], v[210:213], v[70:73]
	v_mfma_f32_16x16x32_bf16 v[126:129], v[152:155], v[190:193], v[126:129]
	v_mfma_f32_16x16x32_bf16 v[118:121], v[160:163], v[190:193], v[118:121]
	v_mfma_f32_16x16x32_bf16 v[110:113], v[152:155], v[198:201], v[110:113]
	v_mfma_f32_16x16x32_bf16 v[102:105], v[160:163], v[198:201], v[102:105]
	v_mfma_f32_16x16x32_bf16 v[94:97], v[152:155], v[206:209], v[94:97]
	v_mfma_f32_16x16x32_bf16 v[86:89], v[160:163], v[206:209], v[86:89]
	v_mfma_f32_16x16x32_bf16 v[78:81], v[152:155], v[214:217], v[78:81]
	v_mfma_f32_16x16x32_bf16 v[70:73], v[160:163], v[214:217], v[70:73]
	v_mfma_f32_16x16x32_bf16 v[122:125], v[170:173], v[186:189], v[122:125]
	v_mfma_f32_16x16x32_bf16 v[114:117], v[178:181], v[186:189], v[114:117]
	v_mfma_f32_16x16x32_bf16 v[106:109], v[170:173], v[194:197], v[106:109]
	v_mfma_f32_16x16x32_bf16 v[98:101], v[178:181], v[194:197], v[98:101]
	v_mfma_f32_16x16x32_bf16 v[90:93], v[170:173], v[202:205], v[90:93]
	v_mfma_f32_16x16x32_bf16 v[82:85], v[178:181], v[202:205], v[82:85]
	v_mfma_f32_16x16x32_bf16 v[74:77], v[170:173], v[210:213], v[74:77]
	v_mfma_f32_16x16x32_bf16 v[66:69], v[178:181], v[210:213], v[66:69]
	v_mfma_f32_16x16x32_bf16 v[122:125], v[174:177], v[190:193], v[122:125]
	v_mfma_f32_16x16x32_bf16 v[114:117], v[182:185], v[190:193], v[114:117]
	v_mfma_f32_16x16x32_bf16 v[106:109], v[174:177], v[198:201], v[106:109]
	v_mfma_f32_16x16x32_bf16 v[98:101], v[182:185], v[198:201], v[98:101]
	v_mfma_f32_16x16x32_bf16 v[90:93], v[174:177], v[206:209], v[90:93]
	v_mfma_f32_16x16x32_bf16 v[82:85], v[182:185], v[206:209], v[82:85]
	v_mfma_f32_16x16x32_bf16 v[74:77], v[174:177], v[214:217], v[74:77]
	v_mfma_f32_16x16x32_bf16 v[66:69], v[182:185], v[214:217], v[66:69]
	s_barrier
	s_add_i32 s98, s74, s24
	s_add_i32 m0, s98, 0xffffff80
	ds_read_b128 v[186:189], v167 offset:49152
	ds_read_b128 v[190:193], v167 offset:50176
	ds_read_b128 v[194:197], v167 offset:51200
	ds_read_b128 v[198:201], v167 offset:52224
	ds_read_b128 v[202:205], v167 offset:53248
	ds_read_b128 v[206:209], v167 offset:54272
	ds_read_b128 v[210:213], v167 offset:55296
	ds_read_b128 v[214:217], v167 offset:56320
	global_load_lds_dwordx4 v134, s[28:29] offset:128
	s_add_i32 m0, s98, 0x1f80
	s_add_i32 s98, s75, s24
	global_load_lds_dwordx4 v130, s[28:29] offset:128
	s_add_u32 s28, s28, 0x40080
	s_addc_u32 s29, s29, 0
	s_mov_b32 m0, s98
	s_nop 0
	global_load_lds_dwordx4 v134, s[28:29]
	s_add_i32 m0, s98, 0x2000
	s_nop 0
	global_load_lds_dwordx4 v130, s[28:29]
	s_add_i32 m0, s56, 0xffffff80
	s_nop 0
	global_load_lds_dwordx4 v136, s[30:31] offset:128
	s_add_i32 m0, s57, 0xffffff80
	s_nop 0
	global_load_lds_dwordx4 v132, s[30:31] offset:128
	s_waitcnt vmcnt(8)
	s_waitcnt lgkmcnt(0)
	s_barrier
	v_mfma_f32_16x16x32_bf16 v[62:65], v[148:151], v[186:189], v[62:65]
	v_mfma_f32_16x16x32_bf16 v[54:57], v[156:159], v[186:189], v[54:57]
	v_mfma_f32_16x16x32_bf16 v[46:49], v[148:151], v[194:197], v[46:49]
	v_mfma_f32_16x16x32_bf16 v[38:41], v[156:159], v[194:197], v[38:41]
	v_mfma_f32_16x16x32_bf16 v[30:33], v[148:151], v[202:205], v[30:33]
	v_mfma_f32_16x16x32_bf16 v[22:25], v[156:159], v[202:205], v[22:25]
	v_mfma_f32_16x16x32_bf16 v[14:17], v[148:151], v[210:213], v[14:17]
	v_mfma_f32_16x16x32_bf16 v[6:9], v[156:159], v[210:213], v[6:9]
	v_mfma_f32_16x16x32_bf16 v[62:65], v[152:155], v[190:193], v[62:65]
	v_mfma_f32_16x16x32_bf16 v[54:57], v[160:163], v[190:193], v[54:57]
	v_mfma_f32_16x16x32_bf16 v[46:49], v[152:155], v[198:201], v[46:49]
	v_mfma_f32_16x16x32_bf16 v[38:41], v[160:163], v[198:201], v[38:41]
	v_mfma_f32_16x16x32_bf16 v[30:33], v[152:155], v[206:209], v[30:33]
	v_mfma_f32_16x16x32_bf16 v[22:25], v[160:163], v[206:209], v[22:25]
	v_mfma_f32_16x16x32_bf16 v[14:17], v[152:155], v[214:217], v[14:17]
	v_mfma_f32_16x16x32_bf16 v[6:9], v[160:163], v[214:217], v[6:9]
	v_mfma_f32_16x16x32_bf16 v[58:61], v[170:173], v[186:189], v[58:61]
	v_mfma_f32_16x16x32_bf16 v[50:53], v[178:181], v[186:189], v[50:53]
	v_mfma_f32_16x16x32_bf16 v[42:45], v[170:173], v[194:197], v[42:45]
	v_mfma_f32_16x16x32_bf16 v[34:37], v[178:181], v[194:197], v[34:37]
	v_mfma_f32_16x16x32_bf16 v[26:29], v[170:173], v[202:205], v[26:29]
	v_mfma_f32_16x16x32_bf16 v[18:21], v[178:181], v[202:205], v[18:21]
	v_mfma_f32_16x16x32_bf16 v[10:13], v[170:173], v[210:213], v[10:13]
	v_mfma_f32_16x16x32_bf16 v[2:5], v[178:181], v[210:213], v[2:5]
	v_mfma_f32_16x16x32_bf16 v[58:61], v[174:177], v[190:193], v[58:61]
	v_mfma_f32_16x16x32_bf16 v[50:53], v[182:185], v[190:193], v[50:53]
	v_mfma_f32_16x16x32_bf16 v[42:45], v[174:177], v[198:201], v[42:45]
	v_mfma_f32_16x16x32_bf16 v[34:37], v[182:185], v[198:201], v[34:37]
	v_mfma_f32_16x16x32_bf16 v[26:29], v[174:177], v[206:209], v[26:29]
	v_mfma_f32_16x16x32_bf16 v[18:21], v[182:185], v[206:209], v[18:21]
	v_mfma_f32_16x16x32_bf16 v[10:13], v[174:177], v[214:217], v[10:13]
	v_mfma_f32_16x16x32_bf16 v[2:5], v[182:185], v[214:217], v[2:5]
	s_barrier
	s_add_i32 s73, s73, 2
	s_add_u32 s52, s52, 0x100
	s_addc_u32 s53, s53, 0
	s_add_u32 s71, s71, 0x100
	s_addc_u32 s72, s72, 0
	s_cmp_gt_u32 s73, 13
	s_cbranch_scc0 .LBB0_170
	s_and_b64 vcc, exec, s[10:11]
	s_cbranch_vccz .LBB0_173
	s_barrier

.LBB0_1692:
	s_lshl_b32 s11, s11, 5
	s_lshl_b32 s9, s10, 6
	s_lshl_b32 s23, s10, 13
	s_and_b32 s10, s11, 0x60
	s_add_i32 s11, s24, s28
	s_mov_b64 s[14:15], 0x80
	v_lshl_add_u64 v[142:143], v[156:157], 0, s[14:15]
	s_mov_b32 m0, s11
	s_add_i32 s13, s11, 0x2000
	s_lshl_b32 s29, s10, 7
	s_waitcnt vmcnt(2)
	s_barrier
	global_load_lds_dwordx4 v[142:143], off
	v_lshl_add_u64 v[144:145], v[158:159], 0, s[14:15]
	s_mov_b32 m0, s13
	v_lshl_add_u64 v[130:131], v[164:165], 0, s[14:15]
	s_add_i32 s12, s22, 0x8000
	v_lshl_add_u64 v[146:147], v[166:167], 0, s[14:15]
	s_add_i32 s14, s22, 0xa000
	global_load_lds_dwordx4 v[144:145], off
	s_mov_b32 m0, s12
	s_add_u32 s30, s4, 0x30080
	global_load_lds_dwordx4 v[130:131], off
	s_mov_b32 m0, s14
	s_addc_u32 s31, s5, 0
	s_add_i32 s15, s25, s28
	global_load_lds_dwordx4 v[146:147], off
	v_lshl_add_u64 v[148:149], s[30:31], 0, v[136:137]
	s_mov_b32 m0, s15
	s_add_i32 s16, s15, 0x2000
	global_load_lds_dwordx4 v[148:149], off
	v_lshl_add_u64 v[150:151], s[30:31], 0, v[140:141]
	s_mov_b32 m0, s16
	v_bfe_u32 v170, v0, 4, 2
	global_load_lds_dwordx4 v[150:151], off
	v_lshlrev_b32_e32 v171, 4, v170
	v_or_b32_e32 v139, v171, v139
	v_bitop3_b32 v139, s29, v139, v168 bitop3:0xf6
	v_lshl_or_b32 v204, v1, 6, v171
	v_add_u32_e32 v171, s19, v139
	s_waitcnt vmcnt(6)
	s_barrier
	v_add_u32_e32 v236, s18, v139
	ds_read_b128 v[172:175], v171
	ds_read_b128 v[176:179], v171 offset:1024
	ds_read_b128 v[180:183], v171 offset:2048
	ds_read_b128 v[184:187], v171 offset:3072
	ds_read_b128 v[188:191], v236
	ds_read_b128 v[192:195], v236 offset:1024
	ds_read_b128 v[196:199], v236 offset:2048
	ds_read_b128 v[200:203], v236 offset:3072
	v_bitop3_b32 v168, v204, s23, v169 bitop3:0xde
	v_add_u32_e32 v252, 0, v168
	v_add_u32_e32 v240, s24, v139
	v_add_u32_e32 v139, s25, v139
	s_add_u32 s30, s2, 0x30080
	s_addc_u32 s31, s3, 0
	s_add_i32 s25, s22, 0xc000
	v_lshl_add_u64 v[168:169], s[30:31], 0, v[132:133]
	s_mov_b32 m0, s25
	s_add_i32 s23, s22, 0xe000
	ds_read_b128 v[204:207], v252
	ds_read_b128 v[208:211], v252 offset:1024
	ds_read_b128 v[212:215], v252 offset:2048
	ds_read_b128 v[216:219], v252 offset:3072
	ds_read_b128 v[220:223], v252 offset:4096
	ds_read_b128 v[224:227], v252 offset:5120
	ds_read_b128 v[228:231], v252 offset:6144
	ds_read_b128 v[232:235], v252 offset:7168
	global_load_lds_dwordx4 v[168:169], off
	v_lshl_add_u64 v[168:169], s[30:31], 0, v[134:135]
	s_mov_b32 m0, s23
	s_nop 0
	global_load_lds_dwordx4 v[168:169], off
	s_waitcnt vmcnt(8)
	s_waitcnt lgkmcnt(0)
	s_barrier
	v_mfma_f32_16x16x32_bf16 v[50:53], v[172:175], v[204:207], v[50:53]
	v_mfma_f32_16x16x32_bf16 v[54:57], v[180:183], v[204:207], v[54:57]
	v_mfma_f32_16x16x32_bf16 v[82:85], v[172:175], v[212:215], v[82:85]
	v_mfma_f32_16x16x32_bf16 v[86:89], v[180:183], v[212:215], v[86:89]
	v_mfma_f32_16x16x32_bf16 v[114:117], v[172:175], v[220:223], v[114:117]
	v_mfma_f32_16x16x32_bf16 v[118:121], v[180:183], v[220:223], v[118:121]
	v_mfma_f32_16x16x32_bf16 v[110:113], v[172:175], v[228:231], v[110:113]
	v_mfma_f32_16x16x32_bf16 v[106:109], v[180:183], v[228:231], v[106:109]
	v_mfma_f32_16x16x32_bf16 v[50:53], v[176:179], v[208:211], v[50:53]
	v_mfma_f32_16x16x32_bf16 v[54:57], v[184:187], v[208:211], v[54:57]
	v_mfma_f32_16x16x32_bf16 v[82:85], v[176:179], v[216:219], v[82:85]
	v_mfma_f32_16x16x32_bf16 v[86:89], v[184:187], v[216:219], v[86:89]
	v_mfma_f32_16x16x32_bf16 v[114:117], v[176:179], v[224:227], v[114:117]
	v_mfma_f32_16x16x32_bf16 v[118:121], v[184:187], v[224:227], v[118:121]
	v_mfma_f32_16x16x32_bf16 v[110:113], v[176:179], v[232:235], v[110:113]
	v_mfma_f32_16x16x32_bf16 v[106:109], v[184:187], v[232:235], v[106:109]
	v_mfma_f32_16x16x32_bf16 v[58:61], v[188:191], v[204:207], v[58:61]
	v_mfma_f32_16x16x32_bf16 v[62:65], v[196:199], v[204:207], v[62:65]
	v_mfma_f32_16x16x32_bf16 v[90:93], v[188:191], v[212:215], v[90:93]
	v_mfma_f32_16x16x32_bf16 v[98:101], v[196:199], v[212:215], v[98:101]
	v_mfma_f32_16x16x32_bf16 v[122:125], v[188:191], v[220:223], v[122:125]
	v_mfma_f32_16x16x32_bf16 v[126:129], v[196:199], v[220:223], v[126:129]
	v_mfma_f32_16x16x32_bf16 v[102:105], v[188:191], v[228:231], v[102:105]
	v_mfma_f32_16x16x32_bf16 v[94:97], v[196:199], v[228:231], v[94:97]
	v_mfma_f32_16x16x32_bf16 v[58:61], v[192:195], v[208:211], v[58:61]
	v_mfma_f32_16x16x32_bf16 v[62:65], v[200:203], v[208:211], v[62:65]
	v_mfma_f32_16x16x32_bf16 v[90:93], v[192:195], v[216:219], v[90:93]
	v_mfma_f32_16x16x32_bf16 v[98:101], v[200:203], v[216:219], v[98:101]
	v_mfma_f32_16x16x32_bf16 v[122:125], v[192:195], v[224:227], v[122:125]
	v_mfma_f32_16x16x32_bf16 v[126:129], v[200:203], v[224:227], v[126:129]
	v_mfma_f32_16x16x32_bf16 v[102:105], v[192:195], v[232:235], v[102:105]
	v_mfma_f32_16x16x32_bf16 v[94:97], v[200:203], v[232:235], v[94:97]
	s_barrier
	s_add_i32 s19, s19, s28
	s_mov_b64 s[30:31], 0x100
	s_add_i32 s24, s19, 0x2000
	v_lshl_add_u64 v[168:169], v[156:157], 0, s[30:31]
	s_mov_b32 m0, s19
	s_add_u32 s34, s4, 0x30100
	ds_read_b128 v[204:207], v252 offset:16384
	ds_read_b128 v[208:211], v252 offset:17408
	ds_read_b128 v[212:215], v252 offset:18432
	ds_read_b128 v[216:219], v252 offset:19456
	ds_read_b128 v[220:223], v252 offset:20480
	ds_read_b128 v[224:227], v252 offset:21504
	ds_read_b128 v[228:231], v252 offset:22528
	ds_read_b128 v[232:235], v252 offset:23552
	global_load_lds_dwordx4 v[168:169], off
	v_lshl_add_u64 v[168:169], v[158:159], 0, s[30:31]
	s_mov_b32 m0, s24
	s_addc_u32 s35, s5, 0
	s_add_i32 s18, s18, s28
	global_load_lds_dwordx4 v[168:169], off
	v_lshl_add_u64 v[168:169], s[34:35], 0, v[136:137]
	s_mov_b32 m0, s18
	s_add_i32 s28, s18, 0x2000
	global_load_lds_dwordx4 v[168:169], off
	v_lshl_add_u64 v[168:169], s[34:35], 0, v[140:141]
	s_mov_b32 m0, s28
	s_nop 0
	global_load_lds_dwordx4 v[168:169], off
	v_lshl_add_u64 v[168:169], v[164:165], 0, s[30:31]
	s_mov_b32 m0, s22
	s_nop 0
	global_load_lds_dwordx4 v[168:169], off
	v_lshl_add_u64 v[168:169], v[166:167], 0, s[30:31]
	s_mov_b32 m0, s21
	s_nop 0
	global_load_lds_dwordx4 v[168:169], off
	s_waitcnt vmcnt(8)
	s_waitcnt lgkmcnt(0)
	s_barrier
	v_mfma_f32_16x16x32_bf16 v[46:49], v[172:175], v[212:215], v[46:49]
	v_mfma_f32_16x16x32_bf16 v[42:45], v[180:183], v[212:215], v[42:45]
	v_mfma_f32_16x16x32_bf16 v[30:33], v[172:175], v[220:223], v[30:33]
	v_mfma_f32_16x16x32_bf16 v[26:29], v[180:183], v[220:223], v[26:29]
	v_mfma_f32_16x16x32_bf16 v[14:17], v[172:175], v[228:231], v[14:17]
	v_mfma_f32_16x16x32_bf16 v[10:13], v[180:183], v[228:231], v[10:13]
	v_mfma_f32_16x16x32_bf16 v[78:81], v[172:175], v[204:207], v[78:81]
	v_mfma_f32_16x16x32_bf16 v[74:77], v[180:183], v[204:207], v[74:77]
	v_mfma_f32_16x16x32_bf16 v[46:49], v[176:179], v[216:219], v[46:49]
	v_mfma_f32_16x16x32_bf16 v[42:45], v[184:187], v[216:219], v[42:45]
	v_mfma_f32_16x16x32_bf16 v[30:33], v[176:179], v[224:227], v[30:33]
	v_mfma_f32_16x16x32_bf16 v[26:29], v[184:187], v[224:227], v[26:29]
	v_mfma_f32_16x16x32_bf16 v[14:17], v[176:179], v[232:235], v[14:17]
	v_mfma_f32_16x16x32_bf16 v[10:13], v[184:187], v[232:235], v[10:13]
	v_mfma_f32_16x16x32_bf16 v[78:81], v[176:179], v[208:211], v[78:81]
	v_mfma_f32_16x16x32_bf16 v[74:77], v[184:187], v[208:211], v[74:77]
	v_mfma_f32_16x16x32_bf16 v[70:73], v[188:191], v[204:207], v[70:73]
	v_mfma_f32_16x16x32_bf16 v[66:69], v[196:199], v[204:207], v[66:69]
	v_mfma_f32_16x16x32_bf16 v[38:41], v[188:191], v[212:215], v[38:41]
	v_mfma_f32_16x16x32_bf16 v[34:37], v[196:199], v[212:215], v[34:37]
	v_mfma_f32_16x16x32_bf16 v[22:25], v[188:191], v[220:223], v[22:25]
	v_mfma_f32_16x16x32_bf16 v[18:21], v[196:199], v[220:223], v[18:21]
	v_mfma_f32_16x16x32_bf16 v[6:9], v[188:191], v[228:231], v[6:9]
	v_mfma_f32_16x16x32_bf16 v[2:5], v[196:199], v[228:231], v[2:5]
	v_mfma_f32_16x16x32_bf16 v[70:73], v[192:195], v[208:211], v[70:73]
	v_mfma_f32_16x16x32_bf16 v[66:69], v[200:203], v[208:211], v[66:69]
	v_mfma_f32_16x16x32_bf16 v[38:41], v[192:195], v[216:219], v[38:41]
	v_mfma_f32_16x16x32_bf16 v[34:37], v[200:203], v[216:219], v[34:37]
	v_mfma_f32_16x16x32_bf16 v[22:25], v[192:195], v[224:227], v[22:25]
	v_mfma_f32_16x16x32_bf16 v[18:21], v[200:203], v[224:227], v[18:21]
	v_mfma_f32_16x16x32_bf16 v[6:9], v[192:195], v[232:235], v[6:9]
	v_mfma_f32_16x16x32_bf16 v[2:5], v[200:203], v[232:235], v[2:5]
	s_barrier
	ds_read_b128 v[172:175], v240
	ds_read_b128 v[176:179], v240 offset:1024
	ds_read_b128 v[180:183], v240 offset:2048
	ds_read_b128 v[184:187], v240 offset:3072
	ds_read_b128 v[188:191], v139
	ds_read_b128 v[192:195], v139 offset:1024
	ds_read_b128 v[196:199], v139 offset:2048
	ds_read_b128 v[200:203], v139 offset:3072
	s_add_u32 s30, s2, 0x30100
	s_addc_u32 s31, s3, 0
	s_mov_b32 m0, s17
	v_lshl_add_u64 v[168:169], s[30:31], 0, v[132:133]
	ds_read_b128 v[204:207], v252 offset:32768
	ds_read_b128 v[208:211], v252 offset:33792
	ds_read_b128 v[212:215], v252 offset:34816
	ds_read_b128 v[216:219], v252 offset:35840
	ds_read_b128 v[220:223], v252 offset:36864
	ds_read_b128 v[224:227], v252 offset:37888
	ds_read_b128 v[228:231], v252 offset:38912
	ds_read_b128 v[232:235], v252 offset:39936
	global_load_lds_dwordx4 v[168:169], off
	v_lshl_add_u64 v[168:169], s[30:31], 0, v[134:135]
	s_mov_b32 m0, s20
	s_nop 0
	global_load_lds_dwordx4 v[168:169], off
	s_waitcnt vmcnt(8)
	s_waitcnt lgkmcnt(0)
	s_barrier
	v_mfma_f32_16x16x32_bf16 v[50:53], v[172:175], v[204:207], v[50:53]
	v_mfma_f32_16x16x32_bf16 v[54:57], v[180:183], v[204:207], v[54:57]
	v_mfma_f32_16x16x32_bf16 v[82:85], v[172:175], v[212:215], v[82:85]
	v_mfma_f32_16x16x32_bf16 v[86:89], v[180:183], v[212:215], v[86:89]
	v_mfma_f32_16x16x32_bf16 v[114:117], v[172:175], v[220:223], v[114:117]
	v_mfma_f32_16x16x32_bf16 v[118:121], v[180:183], v[220:223], v[118:121]
	v_mfma_f32_16x16x32_bf16 v[110:113], v[172:175], v[228:231], v[110:113]
	v_mfma_f32_16x16x32_bf16 v[106:109], v[180:183], v[228:231], v[106:109]
	v_mfma_f32_16x16x32_bf16 v[50:53], v[176:179], v[208:211], v[50:53]
	v_mfma_f32_16x16x32_bf16 v[54:57], v[184:187], v[208:211], v[54:57]
	v_mfma_f32_16x16x32_bf16 v[82:85], v[176:179], v[216:219], v[82:85]
	v_mfma_f32_16x16x32_bf16 v[86:89], v[184:187], v[216:219], v[86:89]
	v_mfma_f32_16x16x32_bf16 v[114:117], v[176:179], v[224:227], v[114:117]
	v_mfma_f32_16x16x32_bf16 v[118:121], v[184:187], v[224:227], v[118:121]
	v_mfma_f32_16x16x32_bf16 v[110:113], v[176:179], v[232:235], v[110:113]
	v_mfma_f32_16x16x32_bf16 v[106:109], v[184:187], v[232:235], v[106:109]
	v_mfma_f32_16x16x32_bf16 v[58:61], v[188:191], v[204:207], v[58:61]
	v_mfma_f32_16x16x32_bf16 v[62:65], v[196:199], v[204:207], v[62:65]
	v_mfma_f32_16x16x32_bf16 v[90:93], v[188:191], v[212:215], v[90:93]
	v_mfma_f32_16x16x32_bf16 v[98:101], v[196:199], v[212:215], v[98:101]
	v_mfma_f32_16x16x32_bf16 v[122:125], v[188:191], v[220:223], v[122:125]
	v_mfma_f32_16x16x32_bf16 v[126:129], v[196:199], v[220:223], v[126:129]
	v_mfma_f32_16x16x32_bf16 v[102:105], v[188:191], v[228:231], v[102:105]
	v_mfma_f32_16x16x32_bf16 v[94:97], v[196:199], v[228:231], v[94:97]
	v_mfma_f32_16x16x32_bf16 v[58:61], v[192:195], v[208:211], v[58:61]
	v_mfma_f32_16x16x32_bf16 v[62:65], v[200:203], v[208:211], v[62:65]
	v_mfma_f32_16x16x32_bf16 v[90:93], v[192:195], v[216:219], v[90:93]
	v_mfma_f32_16x16x32_bf16 v[98:101], v[200:203], v[216:219], v[98:101]
	v_mfma_f32_16x16x32_bf16 v[122:125], v[192:195], v[224:227], v[122:125]
	v_mfma_f32_16x16x32_bf16 v[126:129], v[200:203], v[224:227], v[126:129]
	v_mfma_f32_16x16x32_bf16 v[102:105], v[192:195], v[232:235], v[102:105]
	v_mfma_f32_16x16x32_bf16 v[94:97], v[200:203], v[232:235], v[94:97]
	s_barrier
	s_mov_b64 s[30:31], 0x180
	s_mov_b32 m0, s11
	v_lshl_add_u64 v[168:169], v[156:157], 0, s[30:31]
	s_add_u32 s4, s4, 0x30180
	ds_read_b128 v[204:207], v252 offset:49152
	ds_read_b128 v[208:211], v252 offset:50176
	ds_read_b128 v[212:215], v252 offset:51200
	ds_read_b128 v[216:219], v252 offset:52224
	ds_read_b128 v[220:223], v252 offset:53248
	ds_read_b128 v[224:227], v252 offset:54272
	ds_read_b128 v[228:231], v252 offset:55296
	ds_read_b128 v[232:235], v252 offset:56320
	global_load_lds_dwordx4 v[168:169], off
	v_lshl_add_u64 v[168:169], v[158:159], 0, s[30:31]
	s_mov_b32 m0, s13
	s_addc_u32 s5, s5, 0
	global_load_lds_dwordx4 v[168:169], off
	v_lshl_add_u64 v[136:137], s[4:5], 0, v[136:137]
	s_mov_b32 m0, s15
	s_nop 0
	global_load_lds_dwordx4 v[136:137], off
	v_lshl_add_u64 v[136:137], s[4:5], 0, v[140:141]
	s_mov_b32 m0, s16
	s_nop 0
	global_load_lds_dwordx4 v[136:137], off
	v_lshl_add_u64 v[136:137], v[164:165], 0, s[30:31]
	s_mov_b32 m0, s12
	s_nop 0
	global_load_lds_dwordx4 v[136:137], off
	v_lshl_add_u64 v[136:137], v[166:167], 0, s[30:31]
	s_mov_b32 m0, s14
	s_nop 0
	global_load_lds_dwordx4 v[136:137], off
	s_waitcnt vmcnt(8)
	s_waitcnt lgkmcnt(0)
	s_barrier
	v_mfma_f32_16x16x32_bf16 v[46:49], v[172:175], v[212:215], v[46:49]
	v_mfma_f32_16x16x32_bf16 v[42:45], v[180:183], v[212:215], v[42:45]
	v_mfma_f32_16x16x32_bf16 v[30:33], v[172:175], v[220:223], v[30:33]
	v_mfma_f32_16x16x32_bf16 v[26:29], v[180:183], v[220:223], v[26:29]
	v_mfma_f32_16x16x32_bf16 v[14:17], v[172:175], v[228:231], v[14:17]
	v_mfma_f32_16x16x32_bf16 v[10:13], v[180:183], v[228:231], v[10:13]
	v_mfma_f32_16x16x32_bf16 v[78:81], v[172:175], v[204:207], v[78:81]
	v_mfma_f32_16x16x32_bf16 v[74:77], v[180:183], v[204:207], v[74:77]
	v_mfma_f32_16x16x32_bf16 v[46:49], v[176:179], v[216:219], v[46:49]
	v_mfma_f32_16x16x32_bf16 v[42:45], v[184:187], v[216:219], v[42:45]
	v_mfma_f32_16x16x32_bf16 v[30:33], v[176:179], v[224:227], v[30:33]
	v_mfma_f32_16x16x32_bf16 v[26:29], v[184:187], v[224:227], v[26:29]
	v_mfma_f32_16x16x32_bf16 v[14:17], v[176:179], v[232:235], v[14:17]
	v_mfma_f32_16x16x32_bf16 v[10:13], v[184:187], v[232:235], v[10:13]
	v_mfma_f32_16x16x32_bf16 v[78:81], v[176:179], v[208:211], v[78:81]
	v_mfma_f32_16x16x32_bf16 v[74:77], v[184:187], v[208:211], v[74:77]
	v_mfma_f32_16x16x32_bf16 v[70:73], v[188:191], v[204:207], v[70:73]
	v_mfma_f32_16x16x32_bf16 v[66:69], v[196:199], v[204:207], v[66:69]
	v_mfma_f32_16x16x32_bf16 v[38:41], v[188:191], v[212:215], v[38:41]
	v_mfma_f32_16x16x32_bf16 v[34:37], v[196:199], v[212:215], v[34:37]
	v_mfma_f32_16x16x32_bf16 v[22:25], v[188:191], v[220:223], v[22:25]
	v_mfma_f32_16x16x32_bf16 v[18:21], v[196:199], v[220:223], v[18:21]
	v_mfma_f32_16x16x32_bf16 v[6:9], v[188:191], v[228:231], v[6:9]
	v_mfma_f32_16x16x32_bf16 v[2:5], v[196:199], v[228:231], v[2:5]
	v_mfma_f32_16x16x32_bf16 v[70:73], v[192:195], v[208:211], v[70:73]
	v_mfma_f32_16x16x32_bf16 v[66:69], v[200:203], v[208:211], v[66:69]
	v_mfma_f32_16x16x32_bf16 v[38:41], v[192:195], v[216:219], v[38:41]
	v_mfma_f32_16x16x32_bf16 v[34:37], v[200:203], v[216:219], v[34:37]
	v_mfma_f32_16x16x32_bf16 v[22:25], v[192:195], v[224:227], v[22:25]
	v_mfma_f32_16x16x32_bf16 v[18:21], v[200:203], v[224:227], v[18:21]
	v_mfma_f32_16x16x32_bf16 v[6:9], v[192:195], v[232:235], v[6:9]
	v_mfma_f32_16x16x32_bf16 v[2:5], v[200:203], v[232:235], v[2:5]
	s_barrier
	ds_read_b128 v[172:175], v171
	ds_read_b128 v[176:179], v171 offset:1024
	ds_read_b128 v[180:183], v171 offset:2048
	ds_read_b128 v[184:187], v171 offset:3072
	ds_read_b128 v[188:191], v236
	ds_read_b128 v[192:195], v236 offset:1024
	ds_read_b128 v[196:199], v236 offset:2048
	ds_read_b128 v[200:203], v236 offset:3072
	s_add_u32 s2, s2, 0x30180
	s_addc_u32 s3, s3, 0
	s_mov_b32 m0, s25
	v_lshl_add_u64 v[132:133], s[2:3], 0, v[132:133]
	ds_read_b128 v[204:207], v252
	ds_read_b128 v[208:211], v252 offset:1024
	ds_read_b128 v[212:215], v252 offset:2048
	ds_read_b128 v[216:219], v252 offset:3072
	ds_read_b128 v[220:223], v252 offset:4096
	ds_read_b128 v[224:227], v252 offset:5120
	ds_read_b128 v[228:231], v252 offset:6144
	ds_read_b128 v[232:235], v252 offset:7168
	global_load_lds_dwordx4 v[132:133], off
	v_lshl_add_u64 v[132:133], s[2:3], 0, v[134:135]
	s_mov_b32 m0, s23
	s_nop 0
	global_load_lds_dwordx4 v[132:133], off
	s_waitcnt vmcnt(8)
	s_waitcnt lgkmcnt(0)
	s_barrier
	v_mfma_f32_16x16x32_bf16 v[50:53], v[172:175], v[204:207], v[50:53]
	v_mfma_f32_16x16x32_bf16 v[54:57], v[180:183], v[204:207], v[54:57]
	v_mfma_f32_16x16x32_bf16 v[82:85], v[172:175], v[212:215], v[82:85]
	v_mfma_f32_16x16x32_bf16 v[86:89], v[180:183], v[212:215], v[86:89]
	v_mfma_f32_16x16x32_bf16 v[114:117], v[172:175], v[220:223], v[114:117]
	v_mfma_f32_16x16x32_bf16 v[118:121], v[180:183], v[220:223], v[118:121]
	v_mfma_f32_16x16x32_bf16 v[106:109], v[180:183], v[228:231], v[106:109]
	v_mfma_f32_16x16x32_bf16 v[50:53], v[176:179], v[208:211], v[50:53]
	v_mfma_f32_16x16x32_bf16 v[54:57], v[184:187], v[208:211], v[54:57]
	v_mfma_f32_16x16x32_bf16 v[82:85], v[176:179], v[216:219], v[82:85]
	v_mfma_f32_16x16x32_bf16 v[86:89], v[184:187], v[216:219], v[86:89]
	v_mfma_f32_16x16x32_bf16 v[114:117], v[176:179], v[224:227], v[114:117]
	v_mfma_f32_16x16x32_bf16 v[118:121], v[184:187], v[224:227], v[118:121]
	v_mfma_f32_16x16x32_bf16 v[110:113], v[172:175], v[228:231], v[110:113]
	v_mfma_f32_16x16x32_bf16 v[236:239], v[184:187], v[232:235], v[106:109]
	v_mfma_f32_16x16x32_bf16 v[132:135], v[176:179], v[232:235], v[110:113]
	v_mfma_f32_16x16x32_bf16 v[90:93], v[188:191], v[212:215], v[90:93]
	v_mfma_f32_16x16x32_bf16 v[58:61], v[188:191], v[204:207], v[58:61]
	v_mfma_f32_16x16x32_bf16 v[62:65], v[196:199], v[204:207], v[62:65]
	v_mfma_f32_16x16x32_bf16 v[204:207], v[192:195], v[216:219], v[90:93]
	v_mfma_f32_16x16x32_bf16 v[90:93], v[196:199], v[212:215], v[98:101]
	v_mfma_f32_16x16x32_bf16 v[58:61], v[192:195], v[208:211], v[58:61]
	v_mfma_f32_16x16x32_bf16 v[62:65], v[200:203], v[208:211], v[62:65]
	v_mfma_f32_16x16x32_bf16 v[208:211], v[200:203], v[216:219], v[90:93]
	v_mfma_f32_16x16x32_bf16 v[90:93], v[188:191], v[220:223], v[122:125]
	v_mfma_f32_16x16x32_bf16 v[212:215], v[192:195], v[224:227], v[90:93]
	v_mfma_f32_16x16x32_bf16 v[90:93], v[196:199], v[220:223], v[126:129]
	v_mfma_f32_16x16x32_bf16 v[216:219], v[200:203], v[224:227], v[90:93]
	v_mfma_f32_16x16x32_bf16 v[90:93], v[188:191], v[228:231], v[102:105]
	v_mfma_f32_16x16x32_bf16 v[220:223], v[192:195], v[232:235], v[90:93]
	v_mfma_f32_16x16x32_bf16 v[90:93], v[196:199], v[228:231], v[94:97]
	v_mfma_f32_16x16x32_bf16 v[224:227], v[200:203], v[232:235], v[90:93]
	s_barrier
	s_mov_b32 m0, s19
	s_nop 3
	ds_read_b128 v[90:93], v252 offset:16384
	ds_read_b128 v[94:97], v252 offset:17408
	ds_read_b128 v[98:101], v252 offset:18432
	ds_read_b128 v[102:105], v252 offset:19456
	ds_read_b128 v[106:109], v252 offset:20480
	ds_read_b128 v[110:113], v252 offset:21504
	ds_read_b128 v[122:125], v252 offset:22528
	ds_read_b128 v[126:129], v252 offset:23552
	global_load_lds_dwordx4 v[156:157], off
	s_mov_b32 m0, s24
	s_nop 0
	global_load_lds_dwordx4 v[158:159], off
	s_mov_b32 m0, s18
	s_nop 0
	global_load_lds_dwordx4 v[160:161], off
	s_mov_b32 m0, s28
	s_nop 0
	global_load_lds_dwordx4 v[162:163], off
	s_mov_b32 m0, s22
	s_nop 0
	global_load_lds_dwordx4 v[164:165], off
	s_mov_b32 m0, s21
	s_nop 0
	global_load_lds_dwordx4 v[166:167], off
	s_waitcnt vmcnt(8)
	s_waitcnt lgkmcnt(0)
	s_barrier
	v_mfma_f32_16x16x32_bf16 v[46:49], v[172:175], v[98:101], v[46:49]
	v_mfma_f32_16x16x32_bf16 v[30:33], v[172:175], v[106:109], v[30:33]
	v_mfma_f32_16x16x32_bf16 v[14:17], v[172:175], v[122:125], v[14:17]
	v_mfma_f32_16x16x32_bf16 v[78:81], v[172:175], v[90:93], v[78:81]
	v_mfma_f32_16x16x32_bf16 v[74:77], v[180:183], v[90:93], v[74:77]
	v_mfma_f32_16x16x32_bf16 v[46:49], v[176:179], v[102:105], v[46:49]
	v_mfma_f32_16x16x32_bf16 v[42:45], v[180:183], v[98:101], v[42:45]
	v_mfma_f32_16x16x32_bf16 v[30:33], v[176:179], v[110:113], v[30:33]
	v_mfma_f32_16x16x32_bf16 v[26:29], v[180:183], v[106:109], v[26:29]
	v_mfma_f32_16x16x32_bf16 v[14:17], v[176:179], v[126:129], v[14:17]
	v_mfma_f32_16x16x32_bf16 v[10:13], v[180:183], v[122:125], v[10:13]
	v_mfma_f32_16x16x32_bf16 v[156:159], v[176:179], v[94:97], v[78:81]
	v_mfma_f32_16x16x32_bf16 v[160:163], v[184:187], v[94:97], v[74:77]
	v_mfma_f32_16x16x32_bf16 v[164:167], v[184:187], v[102:105], v[42:45]
	v_mfma_f32_16x16x32_bf16 v[228:231], v[184:187], v[110:113], v[26:29]
	v_mfma_f32_16x16x32_bf16 v[172:175], v[184:187], v[126:129], v[10:13]
	v_mfma_f32_16x16x32_bf16 v[10:13], v[188:191], v[90:93], v[70:73]
	v_mfma_f32_16x16x32_bf16 v[176:179], v[192:195], v[94:97], v[10:13]
	v_mfma_f32_16x16x32_bf16 v[10:13], v[196:199], v[90:93], v[66:69]
	v_mfma_f32_16x16x32_bf16 v[180:183], v[200:203], v[94:97], v[10:13]
	v_mfma_f32_16x16x32_bf16 v[10:13], v[188:191], v[98:101], v[38:41]
	v_mfma_f32_16x16x32_bf16 v[38:41], v[192:195], v[102:105], v[10:13]
	v_mfma_f32_16x16x32_bf16 v[10:13], v[196:199], v[98:101], v[34:37]
	v_mfma_f32_16x16x32_bf16 v[184:187], v[200:203], v[102:105], v[10:13]
	v_mfma_f32_16x16x32_bf16 v[10:13], v[188:191], v[106:109], v[22:25]
	v_mfma_f32_16x16x32_bf16 v[6:9], v[188:191], v[122:125], v[6:9]
	v_mfma_f32_16x16x32_bf16 v[2:5], v[196:199], v[122:125], v[2:5]
	v_mfma_f32_16x16x32_bf16 v[22:25], v[192:195], v[110:113], v[10:13]
	v_mfma_f32_16x16x32_bf16 v[10:13], v[196:199], v[106:109], v[18:21]
	v_mfma_f32_16x16x32_bf16 v[6:9], v[192:195], v[126:129], v[6:9]
	v_mfma_f32_16x16x32_bf16 v[2:5], v[200:203], v[126:129], v[2:5]
	v_mfma_f32_16x16x32_bf16 v[232:235], v[200:203], v[110:113], v[10:13]
	s_barrier
	s_nop 2
	ds_read_b128 v[10:13], v240
	ds_read_b128 v[18:21], v240 offset:1024
	ds_read_b128 v[34:37], v240 offset:2048
	ds_read_b128 v[188:191], v240 offset:3072
	ds_read_b128 v[192:195], v139
	ds_read_b128 v[196:199], v139 offset:1024
	ds_read_b128 v[200:203], v139 offset:2048
	ds_read_b128 v[240:243], v139 offset:3072
	s_mov_b32 m0, s17
	ds_read_b128 v[26:29], v252 offset:32768
	ds_read_b128 v[42:45], v252 offset:33792
	ds_read_b128 v[66:69], v252 offset:34816
	ds_read_b128 v[70:73], v252 offset:35840
	ds_read_b128 v[244:247], v252 offset:36864
	ds_read_b128 v[248:251], v252 offset:37888
	ds_read_b128 v[74:77], v252 offset:38912
	ds_read_b128 v[78:81], v252 offset:39936
	global_load_lds_dwordx4 v[152:153], off
	s_mov_b32 m0, s20
	s_nop 0
	global_load_lds_dwordx4 v[154:155], off
	s_waitcnt vmcnt(8)
	s_waitcnt lgkmcnt(0)
	s_barrier
	v_mfma_f32_16x16x32_bf16 v[50:53], v[10:13], v[26:29], v[50:53]
	v_mfma_f32_16x16x32_bf16 v[122:125], v[18:21], v[42:45], v[50:53]
	v_mfma_f32_16x16x32_bf16 v[50:53], v[34:37], v[26:29], v[54:57]
	v_mfma_f32_16x16x32_bf16 v[126:129], v[188:191], v[42:45], v[50:53]
	v_mfma_f32_16x16x32_bf16 v[50:53], v[10:13], v[66:69], v[82:85]
	v_mfma_f32_16x16x32_bf16 v[106:109], v[18:21], v[70:73], v[50:53]
	v_mfma_f32_16x16x32_bf16 v[50:53], v[34:37], v[66:69], v[86:89]
	v_mfma_f32_16x16x32_bf16 v[110:113], v[188:191], v[70:73], v[50:53]
	v_mfma_f32_16x16x32_bf16 v[50:53], v[10:13], v[244:247], v[114:117]
	v_mfma_f32_16x16x32_bf16 v[90:93], v[18:21], v[248:251], v[50:53]
	v_mfma_f32_16x16x32_bf16 v[50:53], v[34:37], v[244:247], v[118:121]
	v_mfma_f32_16x16x32_bf16 v[94:97], v[188:191], v[248:251], v[50:53]
	v_mfma_f32_16x16x32_bf16 v[50:53], v[10:13], v[74:77], v[132:135]
	v_mfma_f32_16x16x32_bf16 v[152:155], v[18:21], v[78:81], v[50:53]
	v_mfma_f32_16x16x32_bf16 v[50:53], v[34:37], v[74:77], v[236:239]
	v_mfma_f32_16x16x32_bf16 v[236:239], v[188:191], v[78:81], v[50:53]
	v_mfma_f32_16x16x32_bf16 v[50:53], v[192:195], v[26:29], v[58:61]
	v_mfma_f32_16x16x32_bf16 v[26:29], v[200:203], v[26:29], v[62:65]
	v_mfma_f32_16x16x32_bf16 v[118:121], v[240:243], v[42:45], v[26:29]
	v_mfma_f32_16x16x32_bf16 v[26:29], v[192:195], v[66:69], v[204:207]
	v_mfma_f32_16x16x32_bf16 v[98:101], v[196:199], v[70:73], v[26:29]
	v_mfma_f32_16x16x32_bf16 v[26:29], v[200:203], v[66:69], v[208:211]
	v_mfma_f32_16x16x32_bf16 v[102:105], v[240:243], v[70:73], v[26:29]
	v_mfma_f32_16x16x32_bf16 v[26:29], v[192:195], v[244:247], v[212:215]
	v_mfma_f32_16x16x32_bf16 v[82:85], v[196:199], v[248:251], v[26:29]
	v_mfma_f32_16x16x32_bf16 v[26:29], v[200:203], v[244:247], v[216:219]
	v_mfma_f32_16x16x32_bf16 v[86:89], v[240:243], v[248:251], v[26:29]
	v_mfma_f32_16x16x32_bf16 v[26:29], v[192:195], v[74:77], v[220:223]
	v_mfma_f32_16x16x32_bf16 v[66:69], v[196:199], v[78:81], v[26:29]
	v_mfma_f32_16x16x32_bf16 v[26:29], v[200:203], v[74:77], v[224:227]
	v_mfma_f32_16x16x32_bf16 v[114:117], v[196:199], v[42:45], v[50:53]
	v_mfma_f32_16x16x32_bf16 v[70:73], v[240:243], v[78:81], v[26:29]
	s_barrier
	s_mov_b32 m0, s11
	ds_read_b128 v[54:57], v252 offset:49152
	ds_read_b128 v[74:77], v252 offset:50176
	ds_read_b128 v[78:81], v252 offset:51200
	ds_read_b128 v[132:135], v252 offset:52224
	ds_read_b128 v[204:207], v252 offset:53248
	ds_read_b128 v[208:211], v252 offset:54272
	ds_read_b128 v[212:215], v252 offset:55296
	ds_read_b128 v[216:219], v252 offset:56320
	global_load_lds_dwordx4 v[142:143], off
	s_mov_b32 m0, s13
	s_nop 0
	global_load_lds_dwordx4 v[144:145], off
	s_mov_b32 m0, s15
	s_nop 0
	global_load_lds_dwordx4 v[148:149], off
	s_mov_b32 m0, s16
	s_nop 0
	global_load_lds_dwordx4 v[150:151], off
	s_mov_b32 m0, s12
	s_nop 0
	global_load_lds_dwordx4 v[130:131], off
	s_mov_b32 m0, s14
	s_nop 0
	global_load_lds_dwordx4 v[146:147], off
	s_waitcnt vmcnt(8)
	s_waitcnt lgkmcnt(0)
	s_barrier
	v_mfma_f32_16x16x32_bf16 v[26:29], v[10:13], v[54:57], v[156:159]
	v_mfma_f32_16x16x32_bf16 v[58:61], v[18:21], v[74:77], v[26:29]
	v_mfma_f32_16x16x32_bf16 v[26:29], v[34:37], v[54:57], v[160:163]
	v_mfma_f32_16x16x32_bf16 v[62:65], v[188:191], v[74:77], v[26:29]
	v_mfma_f32_16x16x32_bf16 v[26:29], v[10:13], v[78:81], v[46:49]
	v_mfma_f32_16x16x32_bf16 v[42:45], v[18:21], v[132:135], v[26:29]
	v_mfma_f32_16x16x32_bf16 v[26:29], v[34:37], v[78:81], v[164:167]
	v_mfma_f32_16x16x32_bf16 v[46:49], v[188:191], v[132:135], v[26:29]
	v_mfma_f32_16x16x32_bf16 v[26:29], v[10:13], v[204:207], v[30:33]
	v_mfma_f32_16x16x32_bf16 v[30:33], v[34:37], v[204:207], v[228:231]
	v_mfma_f32_16x16x32_bf16 v[10:13], v[10:13], v[212:215], v[14:17]
	v_mfma_f32_16x16x32_bf16 v[14:17], v[34:37], v[212:215], v[172:175]
	v_mfma_f32_16x16x32_bf16 v[26:29], v[18:21], v[208:211], v[26:29]
	v_mfma_f32_16x16x32_bf16 v[30:33], v[188:191], v[208:211], v[30:33]
	v_mfma_f32_16x16x32_bf16 v[10:13], v[18:21], v[216:219], v[10:13]
	v_mfma_f32_16x16x32_bf16 v[14:17], v[188:191], v[216:219], v[14:17]
	v_mfma_f32_16x16x32_bf16 v[18:21], v[192:195], v[54:57], v[176:179]
	v_mfma_f32_16x16x32_bf16 v[50:53], v[196:199], v[74:77], v[18:21]
	v_mfma_f32_16x16x32_bf16 v[18:21], v[200:203], v[54:57], v[180:183]
	v_mfma_f32_16x16x32_bf16 v[54:57], v[240:243], v[74:77], v[18:21]
	v_mfma_f32_16x16x32_bf16 v[18:21], v[192:195], v[78:81], v[38:41]
	v_mfma_f32_16x16x32_bf16 v[34:37], v[196:199], v[132:135], v[18:21]
	v_mfma_f32_16x16x32_bf16 v[18:21], v[200:203], v[78:81], v[184:187]
	v_mfma_f32_16x16x32_bf16 v[38:41], v[240:243], v[132:135], v[18:21]
	v_mfma_f32_16x16x32_bf16 v[18:21], v[192:195], v[204:207], v[22:25]
	v_mfma_f32_16x16x32_bf16 v[22:25], v[200:203], v[204:207], v[232:235]
	v_mfma_f32_16x16x32_bf16 v[6:9], v[192:195], v[212:215], v[6:9]
	v_mfma_f32_16x16x32_bf16 v[2:5], v[200:203], v[212:215], v[2:5]
	v_mfma_f32_16x16x32_bf16 v[18:21], v[196:199], v[208:211], v[18:21]
	v_mfma_f32_16x16x32_bf16 v[22:25], v[240:243], v[208:211], v[22:25]
	v_mfma_f32_16x16x32_bf16 v[6:9], v[196:199], v[216:219], v[6:9]
	v_mfma_f32_16x16x32_bf16 v[2:5], v[240:243], v[216:219], v[2:5]
	s_barrier
	s_cmpk_gt_u32 s8, 0xff
	s_cbranch_scc1 .LBB0_1694
	s_barrier

.LBB0_1905:
	ds_read_b128 v[148:151], v165
	ds_read_b128 v[152:155], v165 offset:1024
	ds_read_b128 v[156:159], v165 offset:2048
	ds_read_b128 v[160:163], v165 offset:3072
	ds_read_b128 v[170:173], v166
	ds_read_b128 v[174:177], v166 offset:1024
	ds_read_b128 v[178:181], v166 offset:2048
	ds_read_b128 v[182:185], v166 offset:3072
	s_add_u32 s28, s58, 0xfffc0080
	s_addc_u32 s29, s59, -1
	s_cmp_eq_u32 s74, 12
	s_cselect_b32 s31, s51, s29
	s_cselect_b32 s30, s60, s28
	s_cselect_b32 s29, s49, s73
	s_cselect_b32 s28, s61, s72
	s_add_i32 m0, s33, 0xc000
	ds_read_b128 v[186:189], v167
	ds_read_b128 v[190:193], v167 offset:1024
	ds_read_b128 v[194:197], v167 offset:2048
	ds_read_b128 v[198:201], v167 offset:3072
	ds_read_b128 v[202:205], v167 offset:4096
	ds_read_b128 v[206:209], v167 offset:5120
	ds_read_b128 v[210:213], v167 offset:6144
	ds_read_b128 v[214:217], v167 offset:7168
	global_load_lds_dwordx4 v140, s[58:59]
	s_add_i32 m0, s33, 0xe000
	s_nop 0
	global_load_lds_dwordx4 v142, s[58:59]
	s_waitcnt vmcnt(8)
	s_waitcnt lgkmcnt(0)
	s_barrier
	v_mfma_f32_16x16x32_bf16 v[126:129], v[148:151], v[186:189], v[126:129]
	v_mfma_f32_16x16x32_bf16 v[118:121], v[156:159], v[186:189], v[118:121]
	v_mfma_f32_16x16x32_bf16 v[110:113], v[148:151], v[194:197], v[110:113]
	v_mfma_f32_16x16x32_bf16 v[102:105], v[156:159], v[194:197], v[102:105]
	v_mfma_f32_16x16x32_bf16 v[94:97], v[148:151], v[202:205], v[94:97]
	v_mfma_f32_16x16x32_bf16 v[86:89], v[156:159], v[202:205], v[86:89]
	v_mfma_f32_16x16x32_bf16 v[78:81], v[148:151], v[210:213], v[78:81]
	v_mfma_f32_16x16x32_bf16 v[70:73], v[156:159], v[210:213], v[70:73]
	v_mfma_f32_16x16x32_bf16 v[126:129], v[152:155], v[190:193], v[126:129]
	v_mfma_f32_16x16x32_bf16 v[118:121], v[160:163], v[190:193], v[118:121]
	v_mfma_f32_16x16x32_bf16 v[110:113], v[152:155], v[198:201], v[110:113]
	v_mfma_f32_16x16x32_bf16 v[102:105], v[160:163], v[198:201], v[102:105]
	v_mfma_f32_16x16x32_bf16 v[94:97], v[152:155], v[206:209], v[94:97]
	v_mfma_f32_16x16x32_bf16 v[86:89], v[160:163], v[206:209], v[86:89]
	v_mfma_f32_16x16x32_bf16 v[78:81], v[152:155], v[214:217], v[78:81]
	v_mfma_f32_16x16x32_bf16 v[70:73], v[160:163], v[214:217], v[70:73]
	v_mfma_f32_16x16x32_bf16 v[122:125], v[170:173], v[186:189], v[122:125]
	v_mfma_f32_16x16x32_bf16 v[114:117], v[178:181], v[186:189], v[114:117]
	v_mfma_f32_16x16x32_bf16 v[106:109], v[170:173], v[194:197], v[106:109]
	v_mfma_f32_16x16x32_bf16 v[98:101], v[178:181], v[194:197], v[98:101]
	v_mfma_f32_16x16x32_bf16 v[90:93], v[170:173], v[202:205], v[90:93]
	v_mfma_f32_16x16x32_bf16 v[82:85], v[178:181], v[202:205], v[82:85]
	v_mfma_f32_16x16x32_bf16 v[74:77], v[170:173], v[210:213], v[74:77]
	v_mfma_f32_16x16x32_bf16 v[66:69], v[178:181], v[210:213], v[66:69]
	v_mfma_f32_16x16x32_bf16 v[122:125], v[174:177], v[190:193], v[122:125]
	v_mfma_f32_16x16x32_bf16 v[114:117], v[182:185], v[190:193], v[114:117]
	v_mfma_f32_16x16x32_bf16 v[106:109], v[174:177], v[198:201], v[106:109]
	v_mfma_f32_16x16x32_bf16 v[98:101], v[182:185], v[198:201], v[98:101]
	v_mfma_f32_16x16x32_bf16 v[90:93], v[174:177], v[206:209], v[90:93]
	v_mfma_f32_16x16x32_bf16 v[82:85], v[182:185], v[206:209], v[82:85]
	v_mfma_f32_16x16x32_bf16 v[74:77], v[174:177], v[214:217], v[74:77]
	v_mfma_f32_16x16x32_bf16 v[66:69], v[182:185], v[214:217], v[66:69]
	s_barrier
	s_add_i32 s75, s67, s23
	s_mov_b32 m0, s75
	ds_read_b128 v[186:189], v167 offset:16384
	ds_read_b128 v[190:193], v167 offset:17408
	ds_read_b128 v[194:197], v167 offset:18432
	ds_read_b128 v[198:201], v167 offset:19456
	ds_read_b128 v[202:205], v167 offset:20480
	ds_read_b128 v[206:209], v167 offset:21504
	ds_read_b128 v[210:213], v167 offset:22528
	ds_read_b128 v[214:217], v167 offset:23552
	global_load_lds_dwordx4 v132, s[28:29]
	s_add_i32 m0, s75, 0x2000
	s_add_u32 s76, s28, 0x40000
	s_addc_u32 s77, s29, 0
	s_add_i32 s75, s68, s23
	global_load_lds_dwordx4 v136, s[28:29]
	s_mov_b32 m0, s75
	s_nop 0
	global_load_lds_dwordx4 v132, s[76:77]
	s_add_i32 m0, s75, 0x2000
	s_nop 0
	global_load_lds_dwordx4 v136, s[76:77]
	s_mov_b32 m0, s33
	s_nop 0
	global_load_lds_dwordx4 v130, s[30:31]
	s_mov_b32 m0, s34
	s_nop 0
	global_load_lds_dwordx4 v134, s[30:31]
	s_waitcnt vmcnt(8)
	s_waitcnt lgkmcnt(0)
	s_barrier
	v_mfma_f32_16x16x32_bf16 v[62:65], v[148:151], v[186:189], v[62:65]
	v_mfma_f32_16x16x32_bf16 v[54:57], v[156:159], v[186:189], v[54:57]
	v_mfma_f32_16x16x32_bf16 v[46:49], v[148:151], v[194:197], v[46:49]
	v_mfma_f32_16x16x32_bf16 v[38:41], v[156:159], v[194:197], v[38:41]
	v_mfma_f32_16x16x32_bf16 v[30:33], v[148:151], v[202:205], v[30:33]
	v_mfma_f32_16x16x32_bf16 v[22:25], v[156:159], v[202:205], v[22:25]
	v_mfma_f32_16x16x32_bf16 v[14:17], v[148:151], v[210:213], v[14:17]
	v_mfma_f32_16x16x32_bf16 v[6:9], v[156:159], v[210:213], v[6:9]
	v_mfma_f32_16x16x32_bf16 v[62:65], v[152:155], v[190:193], v[62:65]
	v_mfma_f32_16x16x32_bf16 v[54:57], v[160:163], v[190:193], v[54:57]
	v_mfma_f32_16x16x32_bf16 v[46:49], v[152:155], v[198:201], v[46:49]
	v_mfma_f32_16x16x32_bf16 v[38:41], v[160:163], v[198:201], v[38:41]
	v_mfma_f32_16x16x32_bf16 v[30:33], v[152:155], v[206:209], v[30:33]
	v_mfma_f32_16x16x32_bf16 v[22:25], v[160:163], v[206:209], v[22:25]
	v_mfma_f32_16x16x32_bf16 v[14:17], v[152:155], v[214:217], v[14:17]
	v_mfma_f32_16x16x32_bf16 v[6:9], v[160:163], v[214:217], v[6:9]
	v_mfma_f32_16x16x32_bf16 v[58:61], v[170:173], v[186:189], v[58:61]
	v_mfma_f32_16x16x32_bf16 v[50:53], v[178:181], v[186:189], v[50:53]
	v_mfma_f32_16x16x32_bf16 v[42:45], v[170:173], v[194:197], v[42:45]
	v_mfma_f32_16x16x32_bf16 v[34:37], v[178:181], v[194:197], v[34:37]
	v_mfma_f32_16x16x32_bf16 v[26:29], v[170:173], v[202:205], v[26:29]
	v_mfma_f32_16x16x32_bf16 v[18:21], v[178:181], v[202:205], v[18:21]
	v_mfma_f32_16x16x32_bf16 v[10:13], v[170:173], v[210:213], v[10:13]
	v_mfma_f32_16x16x32_bf16 v[2:5], v[178:181], v[210:213], v[2:5]
	v_mfma_f32_16x16x32_bf16 v[58:61], v[174:177], v[190:193], v[58:61]
	v_mfma_f32_16x16x32_bf16 v[50:53], v[182:185], v[190:193], v[50:53]
	v_mfma_f32_16x16x32_bf16 v[42:45], v[174:177], v[198:201], v[42:45]
	v_mfma_f32_16x16x32_bf16 v[34:37], v[182:185], v[198:201], v[34:37]
	v_mfma_f32_16x16x32_bf16 v[26:29], v[174:177], v[206:209], v[26:29]
	v_mfma_f32_16x16x32_bf16 v[18:21], v[182:185], v[206:209], v[18:21]
	v_mfma_f32_16x16x32_bf16 v[10:13], v[174:177], v[214:217], v[10:13]
	v_mfma_f32_16x16x32_bf16 v[2:5], v[182:185], v[214:217], v[2:5]
	s_barrier
	s_add_i32 s75, 0, 0x18000
	s_add_i32 s76, 0, 0x1c000
	ds_read_b128 v[148:151], v165 offset:32768
	ds_read_b128 v[152:155], v165 offset:33792
	ds_read_b128 v[156:159], v165 offset:34816
	ds_read_b128 v[160:163], v165 offset:35840
	ds_read_b128 v[170:173], v166 offset:32768
	ds_read_b128 v[174:177], v166 offset:33792
	ds_read_b128 v[178:181], v166 offset:34816
	ds_read_b128 v[182:185], v166 offset:35840
	s_add_u32 s98, s30, 0x40000
	s_addc_u32 s99, s31, 0
	s_mov_b32 m0, s35
	ds_read_b128 v[186:189], v167 offset:32768
	ds_read_b128 v[190:193], v167 offset:33792
	ds_read_b128 v[194:197], v167 offset:34816
	ds_read_b128 v[198:201], v167 offset:35840
	ds_read_b128 v[202:205], v167 offset:36864
	ds_read_b128 v[206:209], v167 offset:37888
	ds_read_b128 v[210:213], v167 offset:38912
	ds_read_b128 v[214:217], v167 offset:39936
	global_load_lds_dwordx4 v130, s[98:99]
	s_mov_b32 m0, s57
	s_nop 0
	global_load_lds_dwordx4 v134, s[98:99]
	s_waitcnt vmcnt(8)
	s_waitcnt lgkmcnt(0)
	s_barrier
	v_mfma_f32_16x16x32_bf16 v[126:129], v[148:151], v[186:189], v[126:129]
	v_mfma_f32_16x16x32_bf16 v[118:121], v[156:159], v[186:189], v[118:121]
	v_mfma_f32_16x16x32_bf16 v[110:113], v[148:151], v[194:197], v[110:113]
	v_mfma_f32_16x16x32_bf16 v[102:105], v[156:159], v[194:197], v[102:105]
	v_mfma_f32_16x16x32_bf16 v[94:97], v[148:151], v[202:205], v[94:97]
	v_mfma_f32_16x16x32_bf16 v[86:89], v[156:159], v[202:205], v[86:89]
	v_mfma_f32_16x16x32_bf16 v[78:81], v[148:151], v[210:213], v[78:81]
	v_mfma_f32_16x16x32_bf16 v[70:73], v[156:159], v[210:213], v[70:73]
	v_mfma_f32_16x16x32_bf16 v[126:129], v[152:155], v[190:193], v[126:129]
	v_mfma_f32_16x16x32_bf16 v[118:121], v[160:163], v[190:193], v[118:121]
	v_mfma_f32_16x16x32_bf16 v[110:113], v[152:155], v[198:201], v[110:113]
	v_mfma_f32_16x16x32_bf16 v[102:105], v[160:163], v[198:201], v[102:105]
	v_mfma_f32_16x16x32_bf16 v[94:97], v[152:155], v[206:209], v[94:97]
	v_mfma_f32_16x16x32_bf16 v[86:89], v[160:163], v[206:209], v[86:89]
	v_mfma_f32_16x16x32_bf16 v[78:81], v[152:155], v[214:217], v[78:81]
	v_mfma_f32_16x16x32_bf16 v[70:73], v[160:163], v[214:217], v[70:73]
	v_mfma_f32_16x16x32_bf16 v[122:125], v[170:173], v[186:189], v[122:125]
	v_mfma_f32_16x16x32_bf16 v[114:117], v[178:181], v[186:189], v[114:117]
	v_mfma_f32_16x16x32_bf16 v[106:109], v[170:173], v[194:197], v[106:109]
	v_mfma_f32_16x16x32_bf16 v[98:101], v[178:181], v[194:197], v[98:101]
	v_mfma_f32_16x16x32_bf16 v[90:93], v[170:173], v[202:205], v[90:93]
	v_mfma_f32_16x16x32_bf16 v[82:85], v[178:181], v[202:205], v[82:85]
	v_mfma_f32_16x16x32_bf16 v[74:77], v[170:173], v[210:213], v[74:77]
	v_mfma_f32_16x16x32_bf16 v[66:69], v[178:181], v[210:213], v[66:69]
	v_mfma_f32_16x16x32_bf16 v[122:125], v[174:177], v[190:193], v[122:125]
	v_mfma_f32_16x16x32_bf16 v[114:117], v[182:185], v[190:193], v[114:117]
	v_mfma_f32_16x16x32_bf16 v[106:109], v[174:177], v[198:201], v[106:109]
	v_mfma_f32_16x16x32_bf16 v[98:101], v[182:185], v[198:201], v[98:101]
	v_mfma_f32_16x16x32_bf16 v[90:93], v[174:177], v[206:209], v[90:93]
	v_mfma_f32_16x16x32_bf16 v[82:85], v[182:185], v[206:209], v[82:85]
	v_mfma_f32_16x16x32_bf16 v[74:77], v[174:177], v[214:217], v[74:77]
	v_mfma_f32_16x16x32_bf16 v[66:69], v[182:185], v[214:217], v[66:69]
	s_barrier
	s_add_i32 s98, s75, s23
	s_add_i32 m0, s98, 0xffffff80
	ds_read_b128 v[186:189], v167 offset:49152
	ds_read_b128 v[190:193], v167 offset:50176
	ds_read_b128 v[194:197], v167 offset:51200
	ds_read_b128 v[198:201], v167 offset:52224
	ds_read_b128 v[202:205], v167 offset:53248
	ds_read_b128 v[206:209], v167 offset:54272
	ds_read_b128 v[210:213], v167 offset:55296
	ds_read_b128 v[214:217], v167 offset:56320
	global_load_lds_dwordx4 v132, s[28:29] offset:128
	s_add_i32 m0, s98, 0x1f80
	s_add_i32 s98, s76, s23
	global_load_lds_dwordx4 v136, s[28:29] offset:128
	s_add_u32 s28, s28, 0x40080
	s_addc_u32 s29, s29, 0
	s_mov_b32 m0, s98
	s_nop 0
	global_load_lds_dwordx4 v132, s[28:29]
	s_add_i32 m0, s98, 0x2000
	s_nop 0
	global_load_lds_dwordx4 v136, s[28:29]
	s_add_i32 m0, s62, 0xffffff80
	s_nop 0
	global_load_lds_dwordx4 v130, s[30:31] offset:128
	s_add_i32 m0, s63, 0xffffff80
	s_nop 0
	global_load_lds_dwordx4 v134, s[30:31] offset:128
	s_waitcnt vmcnt(8)
	s_waitcnt lgkmcnt(0)
	s_barrier
	v_mfma_f32_16x16x32_bf16 v[62:65], v[148:151], v[186:189], v[62:65]
	v_mfma_f32_16x16x32_bf16 v[54:57], v[156:159], v[186:189], v[54:57]
	v_mfma_f32_16x16x32_bf16 v[46:49], v[148:151], v[194:197], v[46:49]
	v_mfma_f32_16x16x32_bf16 v[38:41], v[156:159], v[194:197], v[38:41]
	v_mfma_f32_16x16x32_bf16 v[30:33], v[148:151], v[202:205], v[30:33]
	v_mfma_f32_16x16x32_bf16 v[22:25], v[156:159], v[202:205], v[22:25]
	v_mfma_f32_16x16x32_bf16 v[14:17], v[148:151], v[210:213], v[14:17]
	v_mfma_f32_16x16x32_bf16 v[6:9], v[156:159], v[210:213], v[6:9]
	v_mfma_f32_16x16x32_bf16 v[62:65], v[152:155], v[190:193], v[62:65]
	v_mfma_f32_16x16x32_bf16 v[54:57], v[160:163], v[190:193], v[54:57]
	v_mfma_f32_16x16x32_bf16 v[46:49], v[152:155], v[198:201], v[46:49]
	v_mfma_f32_16x16x32_bf16 v[38:41], v[160:163], v[198:201], v[38:41]
	v_mfma_f32_16x16x32_bf16 v[30:33], v[152:155], v[206:209], v[30:33]
	v_mfma_f32_16x16x32_bf16 v[22:25], v[160:163], v[206:209], v[22:25]
	v_mfma_f32_16x16x32_bf16 v[14:17], v[152:155], v[214:217], v[14:17]
	v_mfma_f32_16x16x32_bf16 v[6:9], v[160:163], v[214:217], v[6:9]
	v_mfma_f32_16x16x32_bf16 v[58:61], v[170:173], v[186:189], v[58:61]
	v_mfma_f32_16x16x32_bf16 v[50:53], v[178:181], v[186:189], v[50:53]
	v_mfma_f32_16x16x32_bf16 v[42:45], v[170:173], v[194:197], v[42:45]
	v_mfma_f32_16x16x32_bf16 v[34:37], v[178:181], v[194:197], v[34:37]
	v_mfma_f32_16x16x32_bf16 v[26:29], v[170:173], v[202:205], v[26:29]
	v_mfma_f32_16x16x32_bf16 v[18:21], v[178:181], v[202:205], v[18:21]
	v_mfma_f32_16x16x32_bf16 v[10:13], v[170:173], v[210:213], v[10:13]
	v_mfma_f32_16x16x32_bf16 v[2:5], v[178:181], v[210:213], v[2:5]
	v_mfma_f32_16x16x32_bf16 v[58:61], v[174:177], v[190:193], v[58:61]
	v_mfma_f32_16x16x32_bf16 v[50:53], v[182:185], v[190:193], v[50:53]
	v_mfma_f32_16x16x32_bf16 v[42:45], v[174:177], v[198:201], v[42:45]
	v_mfma_f32_16x16x32_bf16 v[34:37], v[182:185], v[198:201], v[34:37]
	v_mfma_f32_16x16x32_bf16 v[26:29], v[174:177], v[206:209], v[26:29]
	v_mfma_f32_16x16x32_bf16 v[18:21], v[182:185], v[206:209], v[18:21]
	v_mfma_f32_16x16x32_bf16 v[10:13], v[174:177], v[214:217], v[10:13]
	v_mfma_f32_16x16x32_bf16 v[2:5], v[182:185], v[214:217], v[2:5]
	s_barrier
	s_add_i32 s74, s74, 2
	s_add_u32 s58, s58, 0x100
	s_addc_u32 s59, s59, 0
	s_add_u32 s72, s72, 0x100
	s_addc_u32 s73, s73, 0
	s_cmp_gt_u32 s74, 13
	s_cbranch_scc0 .LBB0_1905
	s_and_b64 vcc, exec, s[42:43]
	s_cbranch_vccz .LBB0_1908
	s_barrier

.LBB0_2235:
	ds_read_b128 v[144:147], v139
	ds_read_b128 v[148:151], v139 offset:1024
	ds_read_b128 v[158:161], v139 offset:2048
	ds_read_b128 v[162:165], v139 offset:3072
	ds_read_b128 v[166:169], v140
	ds_read_b128 v[170:173], v140 offset:1024
	ds_read_b128 v[174:177], v140 offset:2048
	ds_read_b128 v[178:181], v140 offset:3072
	s_add_i32 s18, s44, 0x100
	s_and_b64 s[16:17], s[16:17], exec
	s_cselect_b32 s16, 0, s18
	s_cselect_b32 s17, 0, 0
	s_add_u32 s18, s4, s16
	s_addc_u32 s19, s5, s17
	s_add_u32 s16, s0, s16
	s_addc_u32 s17, s1, s17
	s_add_u32 s44, s4, s44
	s_addc_u32 s45, s5, 0
	s_add_u32 s44, s44, 0xb0080
	s_addc_u32 s45, s45, 0
	s_mov_b32 m0, s38
	v_lshl_add_u64 v[154:155], s[44:45], 0, v[130:131]
	ds_read_b128 v[182:185], v141
	ds_read_b128 v[186:189], v141 offset:1024
	ds_read_b128 v[190:193], v141 offset:2048
	ds_read_b128 v[194:197], v141 offset:3072
	ds_read_b128 v[198:201], v141 offset:4096
	ds_read_b128 v[202:205], v141 offset:5120
	ds_read_b128 v[206:209], v141 offset:6144
	ds_read_b128 v[210:213], v141 offset:7168
	global_load_lds_dwordx4 v[154:155], off
	v_lshl_add_u64 v[154:155], s[44:45], 0, v[134:135]
	s_mov_b32 m0, s39
	s_nop 0
	global_load_lds_dwordx4 v[154:155], off
	s_waitcnt vmcnt(8)
	s_waitcnt lgkmcnt(0)
	s_barrier
	v_mfma_f32_16x16x32_bf16 v[126:129], v[144:147], v[182:185], v[126:129]
	v_mfma_f32_16x16x32_bf16 v[122:125], v[158:161], v[182:185], v[122:125]
	v_mfma_f32_16x16x32_bf16 v[118:121], v[144:147], v[190:193], v[118:121]
	v_mfma_f32_16x16x32_bf16 v[114:117], v[158:161], v[190:193], v[114:117]
	v_mfma_f32_16x16x32_bf16 v[94:97], v[144:147], v[198:201], v[94:97]
	v_mfma_f32_16x16x32_bf16 v[90:93], v[158:161], v[198:201], v[90:93]
	v_mfma_f32_16x16x32_bf16 v[78:81], v[144:147], v[206:209], v[78:81]
	v_mfma_f32_16x16x32_bf16 v[74:77], v[158:161], v[206:209], v[74:77]
	v_mfma_f32_16x16x32_bf16 v[126:129], v[148:151], v[186:189], v[126:129]
	v_mfma_f32_16x16x32_bf16 v[122:125], v[162:165], v[186:189], v[122:125]
	v_mfma_f32_16x16x32_bf16 v[118:121], v[148:151], v[194:197], v[118:121]
	v_mfma_f32_16x16x32_bf16 v[114:117], v[162:165], v[194:197], v[114:117]
	v_mfma_f32_16x16x32_bf16 v[94:97], v[148:151], v[202:205], v[94:97]
	v_mfma_f32_16x16x32_bf16 v[90:93], v[162:165], v[202:205], v[90:93]
	v_mfma_f32_16x16x32_bf16 v[78:81], v[148:151], v[210:213], v[78:81]
	v_mfma_f32_16x16x32_bf16 v[74:77], v[162:165], v[210:213], v[74:77]
	v_mfma_f32_16x16x32_bf16 v[110:113], v[166:169], v[182:185], v[110:113]
	v_mfma_f32_16x16x32_bf16 v[106:109], v[174:177], v[182:185], v[106:109]
	v_mfma_f32_16x16x32_bf16 v[102:105], v[166:169], v[190:193], v[102:105]
	v_mfma_f32_16x16x32_bf16 v[98:101], v[174:177], v[190:193], v[98:101]
	v_mfma_f32_16x16x32_bf16 v[86:89], v[166:169], v[198:201], v[86:89]
	v_mfma_f32_16x16x32_bf16 v[82:85], v[174:177], v[198:201], v[82:85]
	v_mfma_f32_16x16x32_bf16 v[70:73], v[166:169], v[206:209], v[70:73]
	v_mfma_f32_16x16x32_bf16 v[66:69], v[174:177], v[206:209], v[66:69]
	v_mfma_f32_16x16x32_bf16 v[110:113], v[170:173], v[186:189], v[110:113]
	v_mfma_f32_16x16x32_bf16 v[106:109], v[178:181], v[186:189], v[106:109]
	v_mfma_f32_16x16x32_bf16 v[102:105], v[170:173], v[194:197], v[102:105]
	v_mfma_f32_16x16x32_bf16 v[98:101], v[178:181], v[194:197], v[98:101]
	v_mfma_f32_16x16x32_bf16 v[86:89], v[170:173], v[202:205], v[86:89]
	v_mfma_f32_16x16x32_bf16 v[82:85], v[178:181], v[202:205], v[82:85]
	v_mfma_f32_16x16x32_bf16 v[70:73], v[170:173], v[210:213], v[70:73]
	v_mfma_f32_16x16x32_bf16 v[66:69], v[178:181], v[210:213], v[66:69]
	s_barrier
	s_mov_b32 m0, s22
	v_lshl_add_u64 v[154:155], s[16:17], 0, v[132:133]
	s_add_u32 s44, s16, 0xb0000
	ds_read_b128 v[182:185], v141 offset:16384
	ds_read_b128 v[186:189], v141 offset:17408
	ds_read_b128 v[190:193], v141 offset:18432
	ds_read_b128 v[194:197], v141 offset:19456
	ds_read_b128 v[198:201], v141 offset:20480
	ds_read_b128 v[202:205], v141 offset:21504
	ds_read_b128 v[206:209], v141 offset:22528
	ds_read_b128 v[210:213], v141 offset:23552
	global_load_lds_dwordx4 v[154:155], off
	v_lshl_add_u64 v[214:215], s[16:17], 0, v[136:137]
	s_mov_b32 m0, s40
	s_addc_u32 s45, s17, 0
	global_load_lds_dwordx4 v[214:215], off
	v_lshl_add_u64 v[216:217], s[44:45], 0, v[132:133]
	s_mov_b32 m0, s23
	v_lshl_add_u64 v[218:219], s[18:19], 0, v[134:135]
	global_load_lds_dwordx4 v[216:217], off
	v_lshl_add_u64 v[216:217], s[44:45], 0, v[136:137]
	s_mov_b32 m0, s41
	s_nop 0
	global_load_lds_dwordx4 v[216:217], off
	v_lshl_add_u64 v[216:217], s[18:19], 0, v[130:131]
	s_mov_b32 m0, s25
	s_nop 0
	global_load_lds_dwordx4 v[216:217], off
	s_mov_b32 m0, s30
	s_nop 0
	global_load_lds_dwordx4 v[218:219], off
	s_waitcnt vmcnt(8)
	s_waitcnt lgkmcnt(0)
	s_barrier
	v_mfma_f32_16x16x32_bf16 v[62:65], v[144:147], v[182:185], v[62:65]
	v_mfma_f32_16x16x32_bf16 v[58:61], v[158:161], v[182:185], v[58:61]
	v_mfma_f32_16x16x32_bf16 v[46:49], v[144:147], v[190:193], v[46:49]
	v_mfma_f32_16x16x32_bf16 v[42:45], v[158:161], v[190:193], v[42:45]
	v_mfma_f32_16x16x32_bf16 v[30:33], v[144:147], v[198:201], v[30:33]
	v_mfma_f32_16x16x32_bf16 v[26:29], v[158:161], v[198:201], v[26:29]
	v_mfma_f32_16x16x32_bf16 v[14:17], v[144:147], v[206:209], v[14:17]
	v_mfma_f32_16x16x32_bf16 v[10:13], v[158:161], v[206:209], v[10:13]
	v_mfma_f32_16x16x32_bf16 v[62:65], v[148:151], v[186:189], v[62:65]
	v_mfma_f32_16x16x32_bf16 v[58:61], v[162:165], v[186:189], v[58:61]
	v_mfma_f32_16x16x32_bf16 v[46:49], v[148:151], v[194:197], v[46:49]
	v_mfma_f32_16x16x32_bf16 v[42:45], v[162:165], v[194:197], v[42:45]
	v_mfma_f32_16x16x32_bf16 v[30:33], v[148:151], v[202:205], v[30:33]
	v_mfma_f32_16x16x32_bf16 v[26:29], v[162:165], v[202:205], v[26:29]
	v_mfma_f32_16x16x32_bf16 v[14:17], v[148:151], v[210:213], v[14:17]
	v_mfma_f32_16x16x32_bf16 v[10:13], v[162:165], v[210:213], v[10:13]
	v_mfma_f32_16x16x32_bf16 v[54:57], v[166:169], v[182:185], v[54:57]
	v_mfma_f32_16x16x32_bf16 v[50:53], v[174:177], v[182:185], v[50:53]
	v_mfma_f32_16x16x32_bf16 v[38:41], v[166:169], v[190:193], v[38:41]
	v_mfma_f32_16x16x32_bf16 v[34:37], v[174:177], v[190:193], v[34:37]
	v_mfma_f32_16x16x32_bf16 v[22:25], v[166:169], v[198:201], v[22:25]
	v_mfma_f32_16x16x32_bf16 v[18:21], v[174:177], v[198:201], v[18:21]
	v_mfma_f32_16x16x32_bf16 v[6:9], v[166:169], v[206:209], v[6:9]
	v_mfma_f32_16x16x32_bf16 v[2:5], v[174:177], v[206:209], v[2:5]
	v_mfma_f32_16x16x32_bf16 v[54:57], v[170:173], v[186:189], v[54:57]
	v_mfma_f32_16x16x32_bf16 v[50:53], v[178:181], v[186:189], v[50:53]
	v_mfma_f32_16x16x32_bf16 v[38:41], v[170:173], v[194:197], v[38:41]
	v_mfma_f32_16x16x32_bf16 v[34:37], v[178:181], v[194:197], v[34:37]
	v_mfma_f32_16x16x32_bf16 v[22:25], v[170:173], v[202:205], v[22:25]
	v_mfma_f32_16x16x32_bf16 v[18:21], v[178:181], v[202:205], v[18:21]
	v_mfma_f32_16x16x32_bf16 v[6:9], v[170:173], v[210:213], v[6:9]
	v_mfma_f32_16x16x32_bf16 v[2:5], v[178:181], v[210:213], v[2:5]
	s_barrier
	ds_read_b128 v[144:147], v142
	ds_read_b128 v[148:151], v142 offset:1024
	ds_read_b128 v[158:161], v142 offset:2048
	ds_read_b128 v[162:165], v142 offset:3072
	ds_read_b128 v[166:169], v143
	ds_read_b128 v[170:173], v143 offset:1024
	ds_read_b128 v[174:177], v143 offset:2048
	ds_read_b128 v[178:181], v143 offset:3072
	s_add_u32 s18, s18, 0xb0000
	s_addc_u32 s19, s19, 0
	s_mov_b32 m0, s31
	v_lshl_add_u64 v[220:221], s[18:19], 0, v[130:131]
	ds_read_b128 v[182:185], v141 offset:32768
	ds_read_b128 v[186:189], v141 offset:33792
	ds_read_b128 v[190:193], v141 offset:34816
	ds_read_b128 v[194:197], v141 offset:35840
	ds_read_b128 v[198:201], v141 offset:36864
	ds_read_b128 v[202:205], v141 offset:37888
	ds_read_b128 v[206:209], v141 offset:38912
	ds_read_b128 v[210:213], v141 offset:39936
	global_load_lds_dwordx4 v[220:221], off
	v_lshl_add_u64 v[220:221], s[18:19], 0, v[134:135]
	s_mov_b32 m0, s34
	s_nop 0
	global_load_lds_dwordx4 v[220:221], off
	s_waitcnt vmcnt(8)
	s_waitcnt lgkmcnt(0)
	s_barrier
	v_mfma_f32_16x16x32_bf16 v[126:129], v[144:147], v[182:185], v[126:129]
	v_mfma_f32_16x16x32_bf16 v[122:125], v[158:161], v[182:185], v[122:125]
	v_mfma_f32_16x16x32_bf16 v[118:121], v[144:147], v[190:193], v[118:121]
	v_mfma_f32_16x16x32_bf16 v[114:117], v[158:161], v[190:193], v[114:117]
	v_mfma_f32_16x16x32_bf16 v[94:97], v[144:147], v[198:201], v[94:97]
	v_mfma_f32_16x16x32_bf16 v[90:93], v[158:161], v[198:201], v[90:93]
	v_mfma_f32_16x16x32_bf16 v[78:81], v[144:147], v[206:209], v[78:81]
	v_mfma_f32_16x16x32_bf16 v[74:77], v[158:161], v[206:209], v[74:77]
	v_mfma_f32_16x16x32_bf16 v[126:129], v[148:151], v[186:189], v[126:129]
	v_mfma_f32_16x16x32_bf16 v[122:125], v[162:165], v[186:189], v[122:125]
	v_mfma_f32_16x16x32_bf16 v[118:121], v[148:151], v[194:197], v[118:121]
	v_mfma_f32_16x16x32_bf16 v[114:117], v[162:165], v[194:197], v[114:117]
	v_mfma_f32_16x16x32_bf16 v[94:97], v[148:151], v[202:205], v[94:97]
	v_mfma_f32_16x16x32_bf16 v[90:93], v[162:165], v[202:205], v[90:93]
	v_mfma_f32_16x16x32_bf16 v[78:81], v[148:151], v[210:213], v[78:81]
	v_mfma_f32_16x16x32_bf16 v[74:77], v[162:165], v[210:213], v[74:77]
	v_mfma_f32_16x16x32_bf16 v[110:113], v[166:169], v[182:185], v[110:113]
	v_mfma_f32_16x16x32_bf16 v[106:109], v[174:177], v[182:185], v[106:109]
	v_mfma_f32_16x16x32_bf16 v[102:105], v[166:169], v[190:193], v[102:105]
	v_mfma_f32_16x16x32_bf16 v[98:101], v[174:177], v[190:193], v[98:101]
	v_mfma_f32_16x16x32_bf16 v[86:89], v[166:169], v[198:201], v[86:89]
	v_mfma_f32_16x16x32_bf16 v[82:85], v[174:177], v[198:201], v[82:85]
	v_mfma_f32_16x16x32_bf16 v[70:73], v[166:169], v[206:209], v[70:73]
	v_mfma_f32_16x16x32_bf16 v[66:69], v[174:177], v[206:209], v[66:69]
	v_mfma_f32_16x16x32_bf16 v[110:113], v[170:173], v[186:189], v[110:113]
	v_mfma_f32_16x16x32_bf16 v[106:109], v[178:181], v[186:189], v[106:109]
	v_mfma_f32_16x16x32_bf16 v[102:105], v[170:173], v[194:197], v[102:105]
	v_mfma_f32_16x16x32_bf16 v[98:101], v[178:181], v[194:197], v[98:101]
	v_mfma_f32_16x16x32_bf16 v[86:89], v[170:173], v[202:205], v[86:89]
	v_mfma_f32_16x16x32_bf16 v[82:85], v[178:181], v[202:205], v[82:85]
	v_mfma_f32_16x16x32_bf16 v[70:73], v[170:173], v[210:213], v[70:73]
	v_mfma_f32_16x16x32_bf16 v[66:69], v[178:181], v[210:213], v[66:69]
	s_barrier
	s_mov_b32 m0, s28
	v_lshl_add_u64 v[154:155], v[154:155], 0, s[6:7]
	s_add_u32 s16, s16, 0xb0080
	ds_read_b128 v[182:185], v141 offset:49152
	ds_read_b128 v[186:189], v141 offset:50176
	ds_read_b128 v[190:193], v141 offset:51200
	ds_read_b128 v[194:197], v141 offset:52224
	ds_read_b128 v[198:201], v141 offset:53248
	ds_read_b128 v[202:205], v141 offset:54272
	ds_read_b128 v[206:209], v141 offset:55296
	ds_read_b128 v[210:213], v141 offset:56320
	global_load_lds_dwordx4 v[154:155], off
	v_lshl_add_u64 v[154:155], v[214:215], 0, s[6:7]
	s_mov_b32 m0, s42
	s_addc_u32 s17, s17, 0
	global_load_lds_dwordx4 v[154:155], off
	v_lshl_add_u64 v[154:155], s[16:17], 0, v[132:133]
	s_mov_b32 m0, s29
	s_nop 0
	global_load_lds_dwordx4 v[154:155], off
	v_lshl_add_u64 v[154:155], s[16:17], 0, v[136:137]
	s_mov_b32 m0, s43
	s_nop 0
	global_load_lds_dwordx4 v[154:155], off
	v_lshl_add_u64 v[154:155], v[216:217], 0, s[6:7]
	s_mov_b32 m0, s35
	s_nop 0
	global_load_lds_dwordx4 v[154:155], off
	v_lshl_add_u64 v[154:155], v[218:219], 0, s[6:7]
	s_mov_b32 m0, s37
	s_nop 0
	global_load_lds_dwordx4 v[154:155], off
	s_waitcnt vmcnt(8)
	s_waitcnt lgkmcnt(0)
	s_barrier
	v_mfma_f32_16x16x32_bf16 v[62:65], v[144:147], v[182:185], v[62:65]
	v_mfma_f32_16x16x32_bf16 v[58:61], v[158:161], v[182:185], v[58:61]
	v_mfma_f32_16x16x32_bf16 v[46:49], v[144:147], v[190:193], v[46:49]
	v_mfma_f32_16x16x32_bf16 v[42:45], v[158:161], v[190:193], v[42:45]
	v_mfma_f32_16x16x32_bf16 v[30:33], v[144:147], v[198:201], v[30:33]
	v_mfma_f32_16x16x32_bf16 v[26:29], v[158:161], v[198:201], v[26:29]
	v_mfma_f32_16x16x32_bf16 v[14:17], v[144:147], v[206:209], v[14:17]
	v_mfma_f32_16x16x32_bf16 v[10:13], v[158:161], v[206:209], v[10:13]
	v_mfma_f32_16x16x32_bf16 v[62:65], v[148:151], v[186:189], v[62:65]
	v_mfma_f32_16x16x32_bf16 v[58:61], v[162:165], v[186:189], v[58:61]
	v_mfma_f32_16x16x32_bf16 v[46:49], v[148:151], v[194:197], v[46:49]
	v_mfma_f32_16x16x32_bf16 v[42:45], v[162:165], v[194:197], v[42:45]
	v_mfma_f32_16x16x32_bf16 v[30:33], v[148:151], v[202:205], v[30:33]
	v_mfma_f32_16x16x32_bf16 v[26:29], v[162:165], v[202:205], v[26:29]
	v_mfma_f32_16x16x32_bf16 v[14:17], v[148:151], v[210:213], v[14:17]
	v_mfma_f32_16x16x32_bf16 v[10:13], v[162:165], v[210:213], v[10:13]
	v_mfma_f32_16x16x32_bf16 v[54:57], v[166:169], v[182:185], v[54:57]
	v_mfma_f32_16x16x32_bf16 v[50:53], v[174:177], v[182:185], v[50:53]
	v_mfma_f32_16x16x32_bf16 v[38:41], v[166:169], v[190:193], v[38:41]
	v_mfma_f32_16x16x32_bf16 v[34:37], v[174:177], v[190:193], v[34:37]
	v_mfma_f32_16x16x32_bf16 v[22:25], v[166:169], v[198:201], v[22:25]
	v_mfma_f32_16x16x32_bf16 v[18:21], v[174:177], v[198:201], v[18:21]
	v_mfma_f32_16x16x32_bf16 v[6:9], v[166:169], v[206:209], v[6:9]
	v_mfma_f32_16x16x32_bf16 v[2:5], v[174:177], v[206:209], v[2:5]
	v_mfma_f32_16x16x32_bf16 v[54:57], v[170:173], v[186:189], v[54:57]
	v_mfma_f32_16x16x32_bf16 v[50:53], v[178:181], v[186:189], v[50:53]
	v_mfma_f32_16x16x32_bf16 v[38:41], v[170:173], v[194:197], v[38:41]
	v_mfma_f32_16x16x32_bf16 v[34:37], v[178:181], v[194:197], v[34:37]
	v_mfma_f32_16x16x32_bf16 v[22:25], v[170:173], v[202:205], v[22:25]
	v_mfma_f32_16x16x32_bf16 v[18:21], v[178:181], v[202:205], v[18:21]
	v_mfma_f32_16x16x32_bf16 v[6:9], v[170:173], v[210:213], v[6:9]
	v_mfma_f32_16x16x32_bf16 v[2:5], v[178:181], v[210:213], v[2:5]
	s_barrier
	s_and_b64 vcc, exec, s[14:15]
	s_mov_b64 s[16:17], -1
	s_mov_b64 s[14:15], 0
	s_movk_i32 s44, 0x100
	s_cbranch_vccnz .LBB0_2235
	s_waitcnt vmcnt(0)
	s_cmpk_gt_u32 s20, 0xff
	s_cbranch_scc1 .LBB0_2238
	s_barrier
